# one M0 write per group of four LDS-DMAs (instruction offsets 0..3072 move LDS and global address together, lane offsets pre-biased)
# speedup vs baseline: 1.2640x; 1.0137x over previous
; DI int tid512() { int t = threadIdx.x; asm volatile("" : "+v"(t)); return t; }
; DI unsigned voff256(size_t ld) { const int t = tid512(); return (unsigned)(((size_t)(t >> 3) * ld + (t & 7) * 8) * 2); }
; DI void gemm256(const char* a_u, unsigned a_voff, size_t astep, const char* b_u, unsigned b_voff, size_t bstep, int nk, char* smem, f32x16 (&acc)[4][2]) {
;   asm volatile("" : "+s"(nk));
;   const int t = tid512(), lane = t & 63, w = t >> 6, wm = w >> 2, wn = w & 3, r = lane & 31, h = lane >> 5;
;   const int soff = (t >> 3) * LROW + (t & 7) * 16;
;   const int aoff = (128 * wm + r) * LROW + h * 16, boff = T2 + (64 * wn + r) * LROW + h * 16;
;   u32x4 ra[4], rb[4];
; #pragma unroll
;   for (int i = 0; i < 4; ++i) { ra[i] = *(const u32x4*)(a_u + i * astep + a_voff); rb[i] = *(const u32x4*)(b_u + i * bstep + b_voff); }
;   __syncthreads();
; #pragma unroll
;   for (int i = 0; i < 4; ++i) { *(u32x4*)(smem + soff + i * 64 * LROW) = ra[i]; *(u32x4*)(smem + T2 + soff + i * 64 * LROW) = rb[i]; }
;   const int last = nk - 1;
;   {
;     const int k1 = last < 1 ? last : 1;
; #pragma unroll
;     for (int i = 0; i < 4; ++i) { ra[i] = *(const u32x4*)(a_u + i * astep + k1 * 128 + a_voff); rb[i] = *(const u32x4*)(b_u + i * bstep + k1 * 128 + b_voff); }
;   }
;   __syncthreads();
; DI void inproj_phase(const Params& p, int layer, char* smem) {
;     ...
;   for (int i = 0;; ++i) {
;     const int L = tile_of(i, 32 * 24);
;     if (L < 0) break;
;     int tm, tn; tile_mn(L, 32, 24, tm, tn);
;     f32x16 acc[4][2]; zero_acc256(acc);
;     gemm256((const char*)(W + (size_t)(tn * 256) * DM), voff256(DM), (size_t)128 * DM, (const char*)(H + (size_t)(256 + tm * 256) * DM), voff256(DM), (size_t)128 * DM, DM / 64, smem, acc);
.LBB0_188:
	s_mul_hi_u32 s6, s8, 0xaaaaaaab
	s_lshr_b32 s6, s6, 6
	s_lshl_b32 s9, s6, 2
	s_sub_i32 s7, 32, s9
	s_min_i32 s10, s7, 4
	s_abs_i32 s7, s10
	v_cvt_f32_u32_e32 v2, s7
	s_sub_i32 s12, 0, s7
	s_mulk_i32 s6, 0xffa0
	s_add_i32 s6, s6, s8
	v_rcp_iflag_f32_e32 v2, v2
	s_abs_i32 s8, s6
	s_xor_b32 s11, s6, s10
	s_ashr_i32 s11, s11, 31
	v_mul_f32_e32 v2, 0x4f7ffffe, v2
	v_cvt_u32_f32_e32 v2, v2
	s_movk_i32 s16, 0xf000
	v_mov_b32_e32 v37, v181
	v_readfirstlane_b32 s13, v2
	s_mul_i32 s12, s12, s13
	s_mul_hi_u32 s12, s13, s12
	s_add_i32 s13, s13, s12
	s_mul_hi_u32 s12, s8, s13
	s_mul_i32 s13, s12, s7
	s_sub_i32 s8, s8, s13
	s_add_i32 s14, s12, 1
	s_sub_i32 s13, s8, s7
	s_cmp_ge_u32 s8, s7
	s_cselect_b32 s12, s14, s12
	s_cselect_b32 s8, s13, s8
	s_add_i32 s13, s12, 1
	s_cmp_ge_u32 s8, s7
	s_cselect_b32 s7, s13, s12
	s_xor_b32 s7, s7, s11
	s_sub_i32 s7, s7, s11
	s_mul_i32 s10, s7, s10
	s_lshl_b32 s8, s7, 8
	s_sub_i32 s6, s6, s10
	s_add_i32 s6, s6, s9
	s_ashr_i32 s9, s8, 31
	s_lshl_b64 s[8:9], s[8:9], 12
	s_add_u32 s12, s0, s8
	v_mov_b32_e32 v2, v0
	s_addc_u32 s13, s1, s9
	s_lshl_b32 s6, s6, 8
	v_lshlrev_b32_e32 v3, 4, v2
	v_and_b32_e32 v3, 0x70, v3
	v_lshlrev_b32_e32 v2, 9, v2
	s_add_i32 s8, s6, 0x100
	v_and_or_b32 v180, v2, s16, v3
	s_ashr_i32 s9, s8, 31
	v_mov_b32_e32 v2, v0
	s_lshl_b64 s[10:11], s[8:9], 12
	s_add_u32 s14, s92, s10
	v_lshlrev_b32_e32 v3, 4, v2
	v_and_b32_e32 v3, 0x70, v3
	v_lshlrev_b32_e32 v2, 9, v2
	v_lshl_add_u64 v[162:163], s[12:13], 0, v[180:181]
	s_addc_u32 s15, s93, s11
	v_and_or_b32 v36, v2, s16, v3
	v_add_co_u32_e32 v12, vcc, s84, v162
	v_lshl_add_u64 v[164:165], s[14:15], 0, v[36:37]
	s_nop 0
	v_addc_co_u32_e32 v13, vcc, 0, v163, vcc
	v_add_co_u32_e32 v16, vcc, s84, v164
	s_mov_b32 s9, 32
	s_nop 0
	v_addc_co_u32_e32 v17, vcc, 0, v165, vcc
	v_add_co_u32_e32 v20, vcc, s31, v162
	s_add_i32 s10, s9, -1
	s_nop 0
	v_addc_co_u32_e32 v21, vcc, 0, v163, vcc
	s_min_i32 s11, s10, 1
	v_add_co_u32_e32 v24, vcc, s31, v164
	s_lshl_b32 s11, s11, 7
	v_mov_b32_e32 v2, v0
	v_addc_co_u32_e32 v25, vcc, 0, v165, vcc
	s_ashr_i32 s16, s11, 31
	v_lshrrev_b32_e32 v132, 6, v0
	s_nop 0
	v_readfirstlane_b32 s61, v132
	v_and_b32_e32 v132, 63, v0
	v_and_b32_e32 v133, 15, v132
	v_lshrrev_b32_e32 v136, 4, v132
	v_bfe_u32 v137, v133, 1, 3
	v_lshlrev_b32_e32 v133, 7, v133
	s_lshr_b32 s60, s61, 2
	s_lshl_b32 s60, s60, 14
	s_add_i32 s60, s60, 16
	s_and_b32 s62, s61, 3
	s_lshl_b32 s62, s62, 13
	s_add_i32 s62, s62, 0x10010
	v_add_u32_e32 v194, 0, v136
	v_xor_b32_e32 v194, v194, v137
	v_lshl_add_u32 v194, v194, 4, v133
	v_add_u32_e32 v160, s62, v194
	v_add_u32_e32 v194, s60, v194
	v_add_u32_e32 v195, 4, v136
	v_xor_b32_e32 v195, v195, v137
	v_lshl_add_u32 v195, v195, 4, v133
	v_add_u32_e32 v161, s62, v195
	v_add_u32_e32 v195, s60, v195
	v_lshrrev_b32_e32 v133, 3, v132
	s_mov_b32 s60, 0x1000
	v_mul_lo_u32 v133, v133, s60
	v_and_b32_e32 v136, 7, v132
	v_lshrrev_b32_e32 v137, 4, v132
	v_xor_b32_e32 v164, v137, v136
	v_lshl_add_u32 v164, v164, 4, v133
	v_add_u32_e32 v165, 4, v137
	v_xor_b32_e32 v165, v165, v136
	v_lshl_add_u32 v165, v165, 4, v133
	v_add_u32_e32 v165, 0x7c00, v165
	v_xor_b32_e32 v130, v137, v136
	v_lshl_add_u32 v130, v130, 4, v133
	v_add_u32_e32 v130, 0xf800, v130
	v_add_u32_e32 v131, 4, v137
	v_xor_b32_e32 v131, v131, v136
	v_lshl_add_u32 v131, v131, 4, v133
	v_add_u32_e32 v131, 0x17400, v131
	s_mul_i32 s60, s61, 0x20000
	s_add_u32 s52, s12, s60
	s_addc_u32 s53, s13, 0
	s_add_u32 s54, s14, s60
	s_addc_u32 s55, s15, 0
	s_lshl_b32 s58, s61, 12
	s_add_i32 s58, s58, 16
	s_add_i32 s59, s58, 0x10000
	s_mov_b32 s56, 0
	s_mov_b32 s57, 31
	s_add_u32 s64, s52, 0x800000
	s_addc_u32 s65, s53, 0
	s_add_u32 s66, s54, 0x0
	s_addc_u32 s67, s55, 0
	s_and_b64 s[62:63], exec, s[40:41]
	s_cselect_b32 s62, 0, 1
	s_add_i32 s60, s22, 1
	s_mul_i32 s60, s60, s88
	s_add_i32 s60, s60, s33
	s_cmp_lt_u32 s60, 96
	s_cselect_b32 s63, s57, -1
	s_cmp_eq_u32 s62, 1
	s_cselect_b32 s63, -1, s63
	s_cbranch_scc1 .Lg_inproj_first
	s_cmp_eq_u32 s22, 0
	s_cbranch_scc1 .Lg_inproj_first
	s_cmp_lt_u32 s56, s57
	s_cselect_b32 s60, 0x80, 0
	s_add_u32 s52, s52, s60
	s_addc_u32 s53, s53, 0
	s_add_u32 s54, s54, s60
	s_addc_u32 s55, s55, 0
	s_cmp_eq_u32 s56, s63
	s_cselect_b32 s52, s64, s52
	s_cselect_b32 s53, s65, s53
	s_cselect_b32 s54, s66, s54
	s_cselect_b32 s55, s67, s55
	v_mov_b64_e32 v[114:115], 0
	v_mov_b64_e32 v[116:117], 0
	v_mov_b64_e32 v[118:119], 0
	v_mov_b64_e32 v[120:121], 0
	v_mov_b64_e32 v[122:123], 0
	v_mov_b64_e32 v[124:125], 0
	v_mov_b64_e32 v[126:127], 0
	v_mov_b64_e32 v[128:129], 0
	v_mov_b64_e32 v[50:51], 0
	v_mov_b64_e32 v[52:53], 0
	v_mov_b64_e32 v[54:55], 0
	v_mov_b64_e32 v[56:57], 0
	v_mov_b64_e32 v[58:59], 0
	v_mov_b64_e32 v[60:61], 0
	v_mov_b64_e32 v[62:63], 0
	v_mov_b64_e32 v[64:65], 0
	v_mov_b64_e32 v[98:99], 0
	v_mov_b64_e32 v[100:101], 0
	v_mov_b64_e32 v[102:103], 0
	v_mov_b64_e32 v[104:105], 0
	v_mov_b64_e32 v[106:107], 0
	v_mov_b64_e32 v[108:109], 0
	v_mov_b64_e32 v[110:111], 0
	v_mov_b64_e32 v[112:113], 0
	v_mov_b64_e32 v[34:35], 0
	v_mov_b64_e32 v[36:37], 0
	v_mov_b64_e32 v[38:39], 0
	v_mov_b64_e32 v[40:41], 0
	v_mov_b64_e32 v[42:43], 0
	v_mov_b64_e32 v[44:45], 0
	v_mov_b64_e32 v[46:47], 0
	v_mov_b64_e32 v[48:49], 0
	v_mov_b64_e32 v[82:83], 0
	v_mov_b64_e32 v[84:85], 0
	v_mov_b64_e32 v[86:87], 0
	v_mov_b64_e32 v[88:89], 0
	v_mov_b64_e32 v[90:91], 0
	v_mov_b64_e32 v[92:93], 0
	v_mov_b64_e32 v[94:95], 0
	v_mov_b64_e32 v[96:97], 0
	v_mov_b64_e32 v[18:19], 0
	v_mov_b64_e32 v[20:21], 0
	v_mov_b64_e32 v[22:23], 0
	v_mov_b64_e32 v[24:25], 0
	v_mov_b64_e32 v[26:27], 0
	v_mov_b64_e32 v[28:29], 0
	v_mov_b64_e32 v[30:31], 0
	v_mov_b64_e32 v[32:33], 0
	v_mov_b64_e32 v[66:67], 0
	v_mov_b64_e32 v[68:69], 0
	v_mov_b64_e32 v[70:71], 0
	v_mov_b64_e32 v[72:73], 0
	v_mov_b64_e32 v[74:75], 0
	v_mov_b64_e32 v[76:77], 0
	v_mov_b64_e32 v[78:79], 0
	v_mov_b64_e32 v[80:81], 0
	v_mov_b64_e32 v[2:3], 0
	v_mov_b64_e32 v[4:5], 0
	v_mov_b64_e32 v[6:7], 0
	v_mov_b64_e32 v[8:9], 0
	v_mov_b64_e32 v[10:11], 0
	v_mov_b64_e32 v[12:13], 0
	v_mov_b64_e32 v[14:15], 0
	v_mov_b64_e32 v[16:17], 0
	s_branch .Lg_inproj_go
; DI int tid512() { int t = threadIdx.x; asm volatile("" : "+v"(t)); return t; }
; DI void gemm256(const char* a_u, unsigned a_voff, size_t astep, const char* b_u, unsigned b_voff, size_t bstep, int nk, char* smem, f32x16 (&acc)[4][2]) {
;   asm volatile("" : "+s"(nk));
;   const int t = tid512(), lane = t & 63, w = t >> 6, wm = w >> 2, wn = w & 3, r = lane & 31, h = lane >> 5;
;   const int soff = (t >> 3) * LROW + (t & 7) * 16;
;   const int aoff = (128 * wm + r) * LROW + h * 16, boff = T2 + (64 * wn + r) * LROW + h * 16;
;   u32x4 ra[4], rb[4];
; #pragma unroll
;   for (int i = 0; i < 4; ++i) { ra[i] = *(const u32x4*)(a_u + i * astep + a_voff); rb[i] = *(const u32x4*)(b_u + i * bstep + b_voff); }
;   __syncthreads();
; #pragma unroll
;   for (int i = 0; i < 4; ++i) { *(u32x4*)(smem + soff + i * 64 * LROW) = ra[i]; *(u32x4*)(smem + T2 + soff + i * 64 * LROW) = rb[i]; }
;   const int last = nk - 1;
;   {
;     const int k1 = last < 1 ? last : 1;
; #pragma unroll
;     for (int i = 0; i < 4; ++i) { ra[i] = *(const u32x4*)(a_u + i * astep + k1 * 128 + a_voff); rb[i] = *(const u32x4*)(b_u + i * bstep + k1 * 128 + b_voff); }
;   }
;   __syncthreads();
.Lg_inproj_first:
	s_barrier
	s_add_u32 m0, s58, 0x0
	s_nop 0
	global_load_lds_dwordx4 v164, s[52:53]
	global_load_lds_dwordx4 v165, s[52:53] offset:1024
	global_load_lds_dwordx4 v130, s[52:53] offset:2048
	global_load_lds_dwordx4 v131, s[52:53] offset:3072
	s_add_u32 m0, s59, 0x0
	s_nop 0
	global_load_lds_dwordx4 v164, s[54:55]
	global_load_lds_dwordx4 v165, s[54:55] offset:1024
	global_load_lds_dwordx4 v130, s[54:55] offset:2048
	global_load_lds_dwordx4 v131, s[54:55] offset:3072
	s_cmp_lt_u32 s56, s57
	s_cselect_b32 s60, 0x80, 0
	s_add_u32 s52, s52, s60
	s_addc_u32 s53, s53, 0
	s_add_u32 s54, s54, s60
	s_addc_u32 s55, s55, 0
	s_cmp_eq_u32 s56, s63
	s_cselect_b32 s52, s64, s52
	s_cselect_b32 s53, s65, s53
	s_cselect_b32 s54, s66, s54
	s_cselect_b32 s55, s67, s55
	v_mov_b64_e32 v[114:115], 0
	v_mov_b64_e32 v[116:117], 0
	v_mov_b64_e32 v[118:119], 0
	v_mov_b64_e32 v[120:121], 0
	v_mov_b64_e32 v[122:123], 0
	v_mov_b64_e32 v[124:125], 0
	v_mov_b64_e32 v[126:127], 0
	v_mov_b64_e32 v[128:129], 0
	v_mov_b64_e32 v[50:51], 0
	v_mov_b64_e32 v[52:53], 0
	v_mov_b64_e32 v[54:55], 0
	v_mov_b64_e32 v[56:57], 0
	v_mov_b64_e32 v[58:59], 0
	v_mov_b64_e32 v[60:61], 0
	v_mov_b64_e32 v[62:63], 0
	v_mov_b64_e32 v[64:65], 0
	v_mov_b64_e32 v[98:99], 0
	v_mov_b64_e32 v[100:101], 0
	v_mov_b64_e32 v[102:103], 0
	v_mov_b64_e32 v[104:105], 0
	v_mov_b64_e32 v[106:107], 0
	v_mov_b64_e32 v[108:109], 0
	v_mov_b64_e32 v[110:111], 0
	v_mov_b64_e32 v[112:113], 0
	v_mov_b64_e32 v[34:35], 0
	v_mov_b64_e32 v[36:37], 0
	v_mov_b64_e32 v[38:39], 0
	v_mov_b64_e32 v[40:41], 0
	v_mov_b64_e32 v[42:43], 0
	v_mov_b64_e32 v[44:45], 0
	v_mov_b64_e32 v[46:47], 0
	v_mov_b64_e32 v[48:49], 0
	v_mov_b64_e32 v[82:83], 0
	v_mov_b64_e32 v[84:85], 0
	v_mov_b64_e32 v[86:87], 0
	v_mov_b64_e32 v[88:89], 0
	v_mov_b64_e32 v[90:91], 0
	v_mov_b64_e32 v[92:93], 0
	v_mov_b64_e32 v[94:95], 0
	v_mov_b64_e32 v[96:97], 0
	v_mov_b64_e32 v[18:19], 0
	v_mov_b64_e32 v[20:21], 0
	v_mov_b64_e32 v[22:23], 0
	v_mov_b64_e32 v[24:25], 0
	v_mov_b64_e32 v[26:27], 0
	v_mov_b64_e32 v[28:29], 0
	v_mov_b64_e32 v[30:31], 0
	v_mov_b64_e32 v[32:33], 0
	v_mov_b64_e32 v[66:67], 0
	v_mov_b64_e32 v[68:69], 0
	v_mov_b64_e32 v[70:71], 0
	v_mov_b64_e32 v[72:73], 0
	v_mov_b64_e32 v[74:75], 0
	v_mov_b64_e32 v[76:77], 0
	v_mov_b64_e32 v[78:79], 0
	v_mov_b64_e32 v[80:81], 0
	v_mov_b64_e32 v[2:3], 0
	v_mov_b64_e32 v[4:5], 0
	v_mov_b64_e32 v[6:7], 0
	v_mov_b64_e32 v[8:9], 0
	v_mov_b64_e32 v[10:11], 0
	v_mov_b64_e32 v[12:13], 0
	v_mov_b64_e32 v[14:15], 0
	v_mov_b64_e32 v[16:17], 0
	s_waitcnt vmcnt(0)
	s_barrier

; #define MFMA32(a, b, c) __builtin_amdgcn_mfma_f32_32x32x16_bf16((a), (b), (c), 0, 0, 0)
; DI void gemm256(const char* a_u, unsigned a_voff, size_t astep, const char* b_u, unsigned b_voff, size_t bstep, int nk, char* smem, f32x16 (&acc)[4][2]) {
;     ...
;   for (int kt = 0; kt < nk; ++kt) {
;     const int cur = kt & 1, k2 = (kt + 2 < last) ? kt + 2 : last;
;     const char* S = smem + cur * 2 * T2;
;     char* D = smem + (cur ^ 1) * 2 * T2;
;     const char* an = a_u + (size_t)k2 * 128;
;     const char* bn = b_u + (size_t)k2 * 128;
; #pragma unroll
;     for (int s = 0; s < 4; ++s) {
;       bf16x8 a[4], b[2];
; #pragma unroll
;       for (int mi = 0; mi < 4; ++mi) a[mi] = *(const bf16x8*)(S + aoff + mi * 32 * LROW + s * 32);
; #pragma unroll
;       for (int ni = 0; ni < 2; ++ni) b[ni] = *(const bf16x8*)(S + boff + ni * 32 * LROW + s * 32);
;       *(u32x4*)(D + soff + s * 64 * LROW) = ra[s];
;       *(u32x4*)(D + T2 + soff + s * 64 * LROW) = rb[s];
;       ra[s] = *(const u32x4*)(an + s * astep + a_voff);
;       rb[s] = *(const u32x4*)(bn + s * bstep + b_voff);
; #pragma unroll
;       for (int mi = 0; mi < 4; ++mi)
; #pragma unroll
;         for (int ni = 0; ni < 2; ++ni) acc[mi][ni] = MFMA32(a[mi], b[ni], acc[mi][ni]);
;     }
;     __syncthreads();
;   }
.Lg_inproj_loop:
	s_add_i32 s56, s56, 1
	s_add_u32 m0, s59, 0x8000
	s_nop 0
	global_load_lds_dwordx4 v164, s[54:55]
	global_load_lds_dwordx4 v165, s[54:55] offset:1024
	global_load_lds_dwordx4 v130, s[54:55] offset:2048
	global_load_lds_dwordx4 v131, s[54:55] offset:3072
	s_waitcnt lgkmcnt(0)
	v_mfma_f32_16x16x32_bf16 v[114:117], v[196:199], v[212:215], v[114:117]
	ds_read_b128 v[220:223], v194 offset:2048
	v_mfma_f32_16x16x32_bf16 v[118:121], v[196:199], v[216:219], v[118:121]
	ds_read_b128 v[224:227], v194 offset:6144
	v_mfma_f32_16x16x32_bf16 v[50:53], v[196:199], v[242:245], v[50:53]
	ds_read_b128 v[228:231], v194 offset:10240
	v_mfma_f32_16x16x32_bf16 v[54:57], v[196:199], v[246:249], v[54:57]
	ds_read_b128 v[238:241], v194 offset:14336
	v_mfma_f32_16x16x32_bf16 v[98:101], v[200:203], v[212:215], v[98:101]
	v_mfma_f32_16x16x32_bf16 v[102:105], v[200:203], v[216:219], v[102:105]
	v_mfma_f32_16x16x32_bf16 v[34:37], v[200:203], v[242:245], v[34:37]
	v_mfma_f32_16x16x32_bf16 v[38:41], v[200:203], v[246:249], v[38:41]
	v_mfma_f32_16x16x32_bf16 v[82:85], v[204:207], v[212:215], v[82:85]
	v_mfma_f32_16x16x32_bf16 v[86:89], v[204:207], v[216:219], v[86:89]
	v_mfma_f32_16x16x32_bf16 v[18:21], v[204:207], v[242:245], v[18:21]
	v_mfma_f32_16x16x32_bf16 v[22:25], v[204:207], v[246:249], v[22:25]
	v_mfma_f32_16x16x32_bf16 v[66:69], v[208:211], v[212:215], v[66:69]
	v_mfma_f32_16x16x32_bf16 v[70:73], v[208:211], v[216:219], v[70:73]
	v_mfma_f32_16x16x32_bf16 v[2:5], v[208:211], v[242:245], v[2:5]
	v_mfma_f32_16x16x32_bf16 v[6:9], v[208:211], v[246:249], v[6:9]
	s_add_u32 m0, s58, 0x8000
	s_nop 0
	global_load_lds_dwordx4 v164, s[52:53]
	global_load_lds_dwordx4 v165, s[52:53] offset:1024
	global_load_lds_dwordx4 v130, s[52:53] offset:2048
	global_load_lds_dwordx4 v131, s[52:53] offset:3072
	s_waitcnt lgkmcnt(0)
	v_mfma_f32_16x16x32_bf16 v[122:125], v[220:223], v[212:215], v[122:125]
	ds_read_b128 v[196:199], v195 offset:0
	v_mfma_f32_16x16x32_bf16 v[126:129], v[220:223], v[216:219], v[126:129]
	ds_read_b128 v[140:143], v161 offset:0
	v_mfma_f32_16x16x32_bf16 v[58:61], v[220:223], v[242:245], v[58:61]
	ds_read_b128 v[144:147], v161 offset:2048
	v_mfma_f32_16x16x32_bf16 v[62:65], v[220:223], v[246:249], v[62:65]
	ds_read_b128 v[148:151], v161 offset:4096
	v_mfma_f32_16x16x32_bf16 v[106:109], v[224:227], v[212:215], v[106:109]
	ds_read_b128 v[152:155], v161 offset:6144
	v_mfma_f32_16x16x32_bf16 v[110:113], v[224:227], v[216:219], v[110:113]
	ds_read_b128 v[200:203], v195 offset:4096
	v_mfma_f32_16x16x32_bf16 v[42:45], v[224:227], v[242:245], v[42:45]
	ds_read_b128 v[204:207], v195 offset:8192
	v_mfma_f32_16x16x32_bf16 v[46:49], v[224:227], v[246:249], v[46:49]
	ds_read_b128 v[208:211], v195 offset:12288
	v_mfma_f32_16x16x32_bf16 v[90:93], v[228:231], v[212:215], v[90:93]
	v_mfma_f32_16x16x32_bf16 v[94:97], v[228:231], v[216:219], v[94:97]
	v_mfma_f32_16x16x32_bf16 v[26:29], v[228:231], v[242:245], v[26:29]
	v_mfma_f32_16x16x32_bf16 v[30:33], v[228:231], v[246:249], v[30:33]
	v_mfma_f32_16x16x32_bf16 v[74:77], v[238:241], v[212:215], v[74:77]
	v_mfma_f32_16x16x32_bf16 v[78:81], v[238:241], v[216:219], v[78:81]
	v_mfma_f32_16x16x32_bf16 v[10:13], v[238:241], v[242:245], v[10:13]
	v_mfma_f32_16x16x32_bf16 v[14:17], v[238:241], v[246:249], v[14:17]
	s_waitcnt lgkmcnt(0)
	v_mfma_f32_16x16x32_bf16 v[114:117], v[196:199], v[140:143], v[114:117]
	ds_read_b128 v[220:223], v195 offset:2048
	v_mfma_f32_16x16x32_bf16 v[118:121], v[196:199], v[144:147], v[118:121]
	ds_read_b128 v[224:227], v195 offset:6144
	v_mfma_f32_16x16x32_bf16 v[50:53], v[196:199], v[148:151], v[50:53]
	ds_read_b128 v[228:231], v195 offset:10240
	v_mfma_f32_16x16x32_bf16 v[54:57], v[196:199], v[152:155], v[54:57]
	ds_read_b128 v[238:241], v195 offset:14336
	v_mfma_f32_16x16x32_bf16 v[98:101], v[200:203], v[140:143], v[98:101]
	v_mfma_f32_16x16x32_bf16 v[102:105], v[200:203], v[144:147], v[102:105]
	v_mfma_f32_16x16x32_bf16 v[34:37], v[200:203], v[148:151], v[34:37]
	v_mfma_f32_16x16x32_bf16 v[38:41], v[200:203], v[152:155], v[38:41]
	v_mfma_f32_16x16x32_bf16 v[82:85], v[204:207], v[140:143], v[82:85]
	v_mfma_f32_16x16x32_bf16 v[86:89], v[204:207], v[144:147], v[86:89]
	s_cmp_lt_u32 s56, s57
	s_cselect_b32 s60, 0x80, 0
	s_add_u32 s52, s52, s60
	s_addc_u32 s53, s53, 0
	s_add_u32 s54, s54, s60
	s_addc_u32 s55, s55, 0
	s_cmp_eq_u32 s56, s63
	s_cselect_b32 s52, s64, s52
	s_cselect_b32 s53, s65, s53
	s_cselect_b32 s54, s66, s54
	s_cselect_b32 s55, s67, s55
	v_mfma_f32_16x16x32_bf16 v[18:21], v[204:207], v[148:151], v[18:21]
	v_mfma_f32_16x16x32_bf16 v[22:25], v[204:207], v[152:155], v[22:25]
	v_mfma_f32_16x16x32_bf16 v[66:69], v[208:211], v[140:143], v[66:69]
	v_mfma_f32_16x16x32_bf16 v[70:73], v[208:211], v[144:147], v[70:73]
	v_mfma_f32_16x16x32_bf16 v[2:5], v[208:211], v[148:151], v[2:5]
	v_mfma_f32_16x16x32_bf16 v[6:9], v[208:211], v[152:155], v[6:9]
	s_waitcnt lgkmcnt(0)
	v_mfma_f32_16x16x32_bf16 v[122:125], v[220:223], v[140:143], v[122:125]
	v_mfma_f32_16x16x32_bf16 v[126:129], v[220:223], v[144:147], v[126:129]
	v_mfma_f32_16x16x32_bf16 v[58:61], v[220:223], v[148:151], v[58:61]
	v_mfma_f32_16x16x32_bf16 v[62:65], v[220:223], v[152:155], v[62:65]
	v_mfma_f32_16x16x32_bf16 v[106:109], v[224:227], v[140:143], v[106:109]
	v_mfma_f32_16x16x32_bf16 v[110:113], v[224:227], v[144:147], v[110:113]
	v_mfma_f32_16x16x32_bf16 v[42:45], v[224:227], v[148:151], v[42:45]
	v_mfma_f32_16x16x32_bf16 v[46:49], v[224:227], v[152:155], v[46:49]
	v_mfma_f32_16x16x32_bf16 v[90:93], v[228:231], v[140:143], v[90:93]
	v_mfma_f32_16x16x32_bf16 v[94:97], v[228:231], v[144:147], v[94:97]
	v_mfma_f32_16x16x32_bf16 v[26:29], v[228:231], v[148:151], v[26:29]
	v_mfma_f32_16x16x32_bf16 v[30:33], v[228:231], v[152:155], v[30:33]
	v_mfma_f32_16x16x32_bf16 v[74:77], v[238:241], v[140:143], v[74:77]
	v_mfma_f32_16x16x32_bf16 v[78:81], v[238:241], v[144:147], v[78:81]
	v_mfma_f32_16x16x32_bf16 v[10:13], v[238:241], v[148:151], v[10:13]
	v_mfma_f32_16x16x32_bf16 v[14:17], v[238:241], v[152:155], v[14:17]
	s_waitcnt vmcnt(0)
	s_barrier
; #define MFMA32(a, b, c) __builtin_amdgcn_mfma_f32_32x32x16_bf16((a), (b), (c), 0, 0, 0)
; DI void gemm256(const char* a_u, unsigned a_voff, size_t astep, const char* b_u, unsigned b_voff, size_t bstep, int nk, char* smem, f32x16 (&acc)[4][2]) {
;     ...
;   for (int kt = 0; kt < nk; ++kt) {
;     const int cur = kt & 1, k2 = (kt + 2 < last) ? kt + 2 : last;
;     const char* S = smem + cur * 2 * T2;
;     char* D = smem + (cur ^ 1) * 2 * T2;
;     const char* an = a_u + (size_t)k2 * 128;
;     const char* bn = b_u + (size_t)k2 * 128;
; #pragma unroll
;     for (int s = 0; s < 4; ++s) {
;       bf16x8 a[4], b[2];
; #pragma unroll
;       for (int mi = 0; mi < 4; ++mi) a[mi] = *(const bf16x8*)(S + aoff + mi * 32 * LROW + s * 32);
; #pragma unroll
;       for (int ni = 0; ni < 2; ++ni) b[ni] = *(const bf16x8*)(S + boff + ni * 32 * LROW + s * 32);
;       *(u32x4*)(D + soff + s * 64 * LROW) = ra[s];
;       *(u32x4*)(D + T2 + soff + s * 64 * LROW) = rb[s];
;       ra[s] = *(const u32x4*)(an + s * astep + a_voff);
;       rb[s] = *(const u32x4*)(bn + s * bstep + b_voff);
; #pragma unroll
;       for (int mi = 0; mi < 4; ++mi)
; #pragma unroll
;         for (int ni = 0; ni < 2; ++ni) acc[mi][ni] = MFMA32(a[mi], b[ni], acc[mi][ni]);
;     }
;     __syncthreads();
;   }
	ds_read_b128 v[196:199], v194 offset:32768
	ds_read_b128 v[212:215], v160 offset:32768
	ds_read_b128 v[216:219], v160 offset:34816
	ds_read_b128 v[242:245], v160 offset:36864
	ds_read_b128 v[246:249], v160 offset:38912
	ds_read_b128 v[200:203], v194 offset:36864
	ds_read_b128 v[204:207], v194 offset:40960
	ds_read_b128 v[208:211], v194 offset:45056
	s_add_i32 s56, s56, 1
	s_add_u32 m0, s59, 0x0
	s_nop 0
	global_load_lds_dwordx4 v164, s[54:55]
	global_load_lds_dwordx4 v165, s[54:55] offset:1024
	global_load_lds_dwordx4 v130, s[54:55] offset:2048
	global_load_lds_dwordx4 v131, s[54:55] offset:3072
	s_waitcnt lgkmcnt(0)
	v_mfma_f32_16x16x32_bf16 v[114:117], v[196:199], v[212:215], v[114:117]
	ds_read_b128 v[220:223], v194 offset:34816
	v_mfma_f32_16x16x32_bf16 v[118:121], v[196:199], v[216:219], v[118:121]
	ds_read_b128 v[224:227], v194 offset:38912
	v_mfma_f32_16x16x32_bf16 v[50:53], v[196:199], v[242:245], v[50:53]
	ds_read_b128 v[228:231], v194 offset:43008
	v_mfma_f32_16x16x32_bf16 v[54:57], v[196:199], v[246:249], v[54:57]
	ds_read_b128 v[238:241], v194 offset:47104
	v_mfma_f32_16x16x32_bf16 v[98:101], v[200:203], v[212:215], v[98:101]
	v_mfma_f32_16x16x32_bf16 v[102:105], v[200:203], v[216:219], v[102:105]
	v_mfma_f32_16x16x32_bf16 v[34:37], v[200:203], v[242:245], v[34:37]
	v_mfma_f32_16x16x32_bf16 v[38:41], v[200:203], v[246:249], v[38:41]
	v_mfma_f32_16x16x32_bf16 v[82:85], v[204:207], v[212:215], v[82:85]
	v_mfma_f32_16x16x32_bf16 v[86:89], v[204:207], v[216:219], v[86:89]
	v_mfma_f32_16x16x32_bf16 v[18:21], v[204:207], v[242:245], v[18:21]
	v_mfma_f32_16x16x32_bf16 v[22:25], v[204:207], v[246:249], v[22:25]
	v_mfma_f32_16x16x32_bf16 v[66:69], v[208:211], v[212:215], v[66:69]
	v_mfma_f32_16x16x32_bf16 v[70:73], v[208:211], v[216:219], v[70:73]
	v_mfma_f32_16x16x32_bf16 v[2:5], v[208:211], v[242:245], v[2:5]
	v_mfma_f32_16x16x32_bf16 v[6:9], v[208:211], v[246:249], v[6:9]
	s_add_u32 m0, s58, 0x0
	s_nop 0
	global_load_lds_dwordx4 v164, s[52:53]
	global_load_lds_dwordx4 v165, s[52:53] offset:1024
	global_load_lds_dwordx4 v130, s[52:53] offset:2048
	global_load_lds_dwordx4 v131, s[52:53] offset:3072
	s_waitcnt lgkmcnt(0)
	v_mfma_f32_16x16x32_bf16 v[122:125], v[220:223], v[212:215], v[122:125]
	ds_read_b128 v[196:199], v195 offset:32768
	v_mfma_f32_16x16x32_bf16 v[126:129], v[220:223], v[216:219], v[126:129]
	ds_read_b128 v[140:143], v161 offset:32768
	v_mfma_f32_16x16x32_bf16 v[58:61], v[220:223], v[242:245], v[58:61]
	ds_read_b128 v[144:147], v161 offset:34816
	v_mfma_f32_16x16x32_bf16 v[62:65], v[220:223], v[246:249], v[62:65]
	ds_read_b128 v[148:151], v161 offset:36864
	v_mfma_f32_16x16x32_bf16 v[106:109], v[224:227], v[212:215], v[106:109]
	ds_read_b128 v[152:155], v161 offset:38912
	v_mfma_f32_16x16x32_bf16 v[110:113], v[224:227], v[216:219], v[110:113]
	ds_read_b128 v[200:203], v195 offset:36864
	v_mfma_f32_16x16x32_bf16 v[42:45], v[224:227], v[242:245], v[42:45]
	ds_read_b128 v[204:207], v195 offset:40960
	v_mfma_f32_16x16x32_bf16 v[46:49], v[224:227], v[246:249], v[46:49]
	ds_read_b128 v[208:211], v195 offset:45056
	v_mfma_f32_16x16x32_bf16 v[90:93], v[228:231], v[212:215], v[90:93]
	v_mfma_f32_16x16x32_bf16 v[94:97], v[228:231], v[216:219], v[94:97]
	v_mfma_f32_16x16x32_bf16 v[26:29], v[228:231], v[242:245], v[26:29]
	v_mfma_f32_16x16x32_bf16 v[30:33], v[228:231], v[246:249], v[30:33]
	v_mfma_f32_16x16x32_bf16 v[74:77], v[238:241], v[212:215], v[74:77]
	v_mfma_f32_16x16x32_bf16 v[78:81], v[238:241], v[216:219], v[78:81]
	v_mfma_f32_16x16x32_bf16 v[10:13], v[238:241], v[242:245], v[10:13]
	v_mfma_f32_16x16x32_bf16 v[14:17], v[238:241], v[246:249], v[14:17]
	s_waitcnt lgkmcnt(0)
	v_mfma_f32_16x16x32_bf16 v[114:117], v[196:199], v[140:143], v[114:117]
	ds_read_b128 v[220:223], v195 offset:34816
	v_mfma_f32_16x16x32_bf16 v[118:121], v[196:199], v[144:147], v[118:121]
	ds_read_b128 v[224:227], v195 offset:38912
	v_mfma_f32_16x16x32_bf16 v[50:53], v[196:199], v[148:151], v[50:53]
	ds_read_b128 v[228:231], v195 offset:43008
	v_mfma_f32_16x16x32_bf16 v[54:57], v[196:199], v[152:155], v[54:57]
	ds_read_b128 v[238:241], v195 offset:47104
	v_mfma_f32_16x16x32_bf16 v[98:101], v[200:203], v[140:143], v[98:101]
	v_mfma_f32_16x16x32_bf16 v[102:105], v[200:203], v[144:147], v[102:105]
	v_mfma_f32_16x16x32_bf16 v[34:37], v[200:203], v[148:151], v[34:37]
	v_mfma_f32_16x16x32_bf16 v[38:41], v[200:203], v[152:155], v[38:41]
	v_mfma_f32_16x16x32_bf16 v[82:85], v[204:207], v[140:143], v[82:85]
	v_mfma_f32_16x16x32_bf16 v[86:89], v[204:207], v[144:147], v[86:89]
	s_cmp_lt_u32 s56, s57
	s_cselect_b32 s60, 0x80, 0
	s_add_u32 s52, s52, s60
	s_addc_u32 s53, s53, 0
	s_add_u32 s54, s54, s60
	s_addc_u32 s55, s55, 0
	s_cmp_eq_u32 s56, s63
	s_cselect_b32 s52, s64, s52
	s_cselect_b32 s53, s65, s53
	s_cselect_b32 s54, s66, s54
	s_cselect_b32 s55, s67, s55
	v_mfma_f32_16x16x32_bf16 v[18:21], v[204:207], v[148:151], v[18:21]
	v_mfma_f32_16x16x32_bf16 v[22:25], v[204:207], v[152:155], v[22:25]
	v_mfma_f32_16x16x32_bf16 v[66:69], v[208:211], v[140:143], v[66:69]
	v_mfma_f32_16x16x32_bf16 v[70:73], v[208:211], v[144:147], v[70:73]
	v_mfma_f32_16x16x32_bf16 v[2:5], v[208:211], v[148:151], v[2:5]
	v_mfma_f32_16x16x32_bf16 v[6:9], v[208:211], v[152:155], v[6:9]
	s_waitcnt lgkmcnt(0)
	v_mfma_f32_16x16x32_bf16 v[122:125], v[220:223], v[140:143], v[122:125]
	v_mfma_f32_16x16x32_bf16 v[126:129], v[220:223], v[144:147], v[126:129]
	v_mfma_f32_16x16x32_bf16 v[58:61], v[220:223], v[148:151], v[58:61]
	v_mfma_f32_16x16x32_bf16 v[62:65], v[220:223], v[152:155], v[62:65]
	v_mfma_f32_16x16x32_bf16 v[106:109], v[224:227], v[140:143], v[106:109]
	v_mfma_f32_16x16x32_bf16 v[110:113], v[224:227], v[144:147], v[110:113]
	v_mfma_f32_16x16x32_bf16 v[42:45], v[224:227], v[148:151], v[42:45]
	v_mfma_f32_16x16x32_bf16 v[46:49], v[224:227], v[152:155], v[46:49]
	v_mfma_f32_16x16x32_bf16 v[90:93], v[228:231], v[140:143], v[90:93]
	v_mfma_f32_16x16x32_bf16 v[94:97], v[228:231], v[144:147], v[94:97]
	v_mfma_f32_16x16x32_bf16 v[26:29], v[228:231], v[148:151], v[26:29]
	v_mfma_f32_16x16x32_bf16 v[30:33], v[228:231], v[152:155], v[30:33]
	v_mfma_f32_16x16x32_bf16 v[74:77], v[238:241], v[140:143], v[74:77]
	v_mfma_f32_16x16x32_bf16 v[78:81], v[238:241], v[144:147], v[78:81]
	v_mfma_f32_16x16x32_bf16 v[10:13], v[238:241], v[148:151], v[10:13]
	v_mfma_f32_16x16x32_bf16 v[14:17], v[238:241], v[152:155], v[14:17]
	s_waitcnt vmcnt(0)
	s_barrier
; #define MFMA32(a, b, c) __builtin_amdgcn_mfma_f32_32x32x16_bf16((a), (b), (c), 0, 0, 0)
; DI void gemm256(const char* a_u, unsigned a_voff, size_t astep, const char* b_u, unsigned b_voff, size_t bstep, int nk, char* smem, f32x16 (&acc)[4][2]) {
;     ...
;   for (int kt = 0; kt < nk; ++kt) {
;     const int cur = kt & 1, k2 = (kt + 2 < last) ? kt + 2 : last;
;     const char* S = smem + cur * 2 * T2;
;     char* D = smem + (cur ^ 1) * 2 * T2;
;     const char* an = a_u + (size_t)k2 * 128;
;     const char* bn = b_u + (size_t)k2 * 128;
; #pragma unroll
;     for (int s = 0; s < 4; ++s) {
;       bf16x8 a[4], b[2];
; #pragma unroll
;       for (int mi = 0; mi < 4; ++mi) a[mi] = *(const bf16x8*)(S + aoff + mi * 32 * LROW + s * 32);
; #pragma unroll
;       for (int ni = 0; ni < 2; ++ni) b[ni] = *(const bf16x8*)(S + boff + ni * 32 * LROW + s * 32);
;       *(u32x4*)(D + soff + s * 64 * LROW) = ra[s];
;       *(u32x4*)(D + T2 + soff + s * 64 * LROW) = rb[s];
;       ra[s] = *(const u32x4*)(an + s * astep + a_voff);
;       rb[s] = *(const u32x4*)(bn + s * bstep + b_voff);
; #pragma unroll
;       for (int mi = 0; mi < 4; ++mi)
; #pragma unroll
;         for (int ni = 0; ni < 2; ++ni) acc[mi][ni] = MFMA32(a[mi], b[ni], acc[mi][ni]);
;     }
;     __syncthreads();
;   }
	ds_read_b128 v[196:199], v194 offset:0
	ds_read_b128 v[212:215], v160 offset:0
	ds_read_b128 v[216:219], v160 offset:2048
	ds_read_b128 v[242:245], v160 offset:4096
	ds_read_b128 v[246:249], v160 offset:6144
	ds_read_b128 v[200:203], v194 offset:4096
	ds_read_b128 v[204:207], v194 offset:8192
	ds_read_b128 v[208:211], v194 offset:12288
	s_cmp_lt_u32 s56, s57
	s_cbranch_scc1 .Lg_inproj_loop
	s_waitcnt vmcnt(0) lgkmcnt(0)
	s_nop 7
	s_nop 7
	v_permlane16_swap_b32_e32 v114, v118
	v_permlane16_swap_b32_e32 v115, v119
	v_permlane16_swap_b32_e32 v116, v120
	v_permlane16_swap_b32_e32 v117, v121
	v_permlane16_swap_b32_e32 v122, v126
	v_permlane16_swap_b32_e32 v123, v127
	v_permlane16_swap_b32_e32 v124, v128
	v_permlane16_swap_b32_e32 v125, v129
	v_permlane16_swap_b32_e32 v50, v54
	v_permlane16_swap_b32_e32 v51, v55
	v_permlane16_swap_b32_e32 v52, v56
	v_permlane16_swap_b32_e32 v53, v57
	v_permlane16_swap_b32_e32 v58, v62
	v_permlane16_swap_b32_e32 v59, v63
	v_permlane16_swap_b32_e32 v60, v64
	v_permlane16_swap_b32_e32 v61, v65
	v_permlane16_swap_b32_e32 v98, v102
	v_permlane16_swap_b32_e32 v99, v103
	v_permlane16_swap_b32_e32 v100, v104
	v_permlane16_swap_b32_e32 v101, v105
	v_permlane16_swap_b32_e32 v106, v110
	v_permlane16_swap_b32_e32 v107, v111
	v_permlane16_swap_b32_e32 v108, v112
	v_permlane16_swap_b32_e32 v109, v113
	v_permlane16_swap_b32_e32 v34, v38
	v_permlane16_swap_b32_e32 v35, v39
	v_permlane16_swap_b32_e32 v36, v40
	v_permlane16_swap_b32_e32 v37, v41
	v_permlane16_swap_b32_e32 v42, v46
	v_permlane16_swap_b32_e32 v43, v47
	v_permlane16_swap_b32_e32 v44, v48
	v_permlane16_swap_b32_e32 v45, v49
	v_permlane16_swap_b32_e32 v82, v86
	v_permlane16_swap_b32_e32 v83, v87
	v_permlane16_swap_b32_e32 v84, v88
	v_permlane16_swap_b32_e32 v85, v89
	v_permlane16_swap_b32_e32 v90, v94
	v_permlane16_swap_b32_e32 v91, v95
	v_permlane16_swap_b32_e32 v92, v96
	v_permlane16_swap_b32_e32 v93, v97
	v_permlane16_swap_b32_e32 v18, v22
	v_permlane16_swap_b32_e32 v19, v23
	v_permlane16_swap_b32_e32 v20, v24
	v_permlane16_swap_b32_e32 v21, v25
	v_permlane16_swap_b32_e32 v26, v30
	v_permlane16_swap_b32_e32 v27, v31
	v_permlane16_swap_b32_e32 v28, v32
	v_permlane16_swap_b32_e32 v29, v33
	v_permlane16_swap_b32_e32 v66, v70
	v_permlane16_swap_b32_e32 v67, v71
	v_permlane16_swap_b32_e32 v68, v72
	v_permlane16_swap_b32_e32 v69, v73
	v_permlane16_swap_b32_e32 v74, v78
	v_permlane16_swap_b32_e32 v75, v79
	v_permlane16_swap_b32_e32 v76, v80
	v_permlane16_swap_b32_e32 v77, v81
	v_permlane16_swap_b32_e32 v2, v6
	v_permlane16_swap_b32_e32 v3, v7
	v_permlane16_swap_b32_e32 v4, v8
	v_permlane16_swap_b32_e32 v5, v9
	v_permlane16_swap_b32_e32 v10, v14
	v_permlane16_swap_b32_e32 v11, v15
	v_permlane16_swap_b32_e32 v12, v16
	v_permlane16_swap_b32_e32 v13, v17
	v_permlane32_swap_b32_e32 v114, v118
	v_permlane32_swap_b32_e32 v115, v119
	v_permlane32_swap_b32_e32 v116, v120
	v_permlane32_swap_b32_e32 v117, v121
	v_permlane32_swap_b32_e32 v122, v126
	v_permlane32_swap_b32_e32 v123, v127
	v_permlane32_swap_b32_e32 v124, v128
	v_permlane32_swap_b32_e32 v125, v129
	v_permlane32_swap_b32_e32 v50, v54
	v_permlane32_swap_b32_e32 v51, v55
	v_permlane32_swap_b32_e32 v52, v56
	v_permlane32_swap_b32_e32 v53, v57
	v_permlane32_swap_b32_e32 v58, v62
	v_permlane32_swap_b32_e32 v59, v63
	v_permlane32_swap_b32_e32 v60, v64
	v_permlane32_swap_b32_e32 v61, v65
	v_permlane32_swap_b32_e32 v98, v102
	v_permlane32_swap_b32_e32 v99, v103
	v_permlane32_swap_b32_e32 v100, v104
	v_permlane32_swap_b32_e32 v101, v105
	v_permlane32_swap_b32_e32 v106, v110
	v_permlane32_swap_b32_e32 v107, v111
	v_permlane32_swap_b32_e32 v108, v112
	v_permlane32_swap_b32_e32 v109, v113
	v_permlane32_swap_b32_e32 v34, v38
	v_permlane32_swap_b32_e32 v35, v39
	v_permlane32_swap_b32_e32 v36, v40
	v_permlane32_swap_b32_e32 v37, v41
	v_permlane32_swap_b32_e32 v42, v46
	v_permlane32_swap_b32_e32 v43, v47
	v_permlane32_swap_b32_e32 v44, v48
	v_permlane32_swap_b32_e32 v45, v49
	v_permlane32_swap_b32_e32 v82, v86
	v_permlane32_swap_b32_e32 v83, v87
	v_permlane32_swap_b32_e32 v84, v88
	v_permlane32_swap_b32_e32 v85, v89
	v_permlane32_swap_b32_e32 v90, v94
	v_permlane32_swap_b32_e32 v91, v95
	v_permlane32_swap_b32_e32 v92, v96
	v_permlane32_swap_b32_e32 v93, v97
	v_permlane32_swap_b32_e32 v18, v22
	v_permlane32_swap_b32_e32 v19, v23
	v_permlane32_swap_b32_e32 v20, v24
	v_permlane32_swap_b32_e32 v21, v25
	v_permlane32_swap_b32_e32 v26, v30
	v_permlane32_swap_b32_e32 v27, v31
	v_permlane32_swap_b32_e32 v28, v32
	v_permlane32_swap_b32_e32 v29, v33
	v_permlane32_swap_b32_e32 v66, v70
	v_permlane32_swap_b32_e32 v67, v71
	v_permlane32_swap_b32_e32 v68, v72
	v_permlane32_swap_b32_e32 v69, v73
	v_permlane32_swap_b32_e32 v74, v78
	v_permlane32_swap_b32_e32 v75, v79
	v_permlane32_swap_b32_e32 v76, v80
	v_permlane32_swap_b32_e32 v77, v81
	v_permlane32_swap_b32_e32 v2, v6
	v_permlane32_swap_b32_e32 v3, v7
	v_permlane32_swap_b32_e32 v4, v8
	v_permlane32_swap_b32_e32 v5, v9
	v_permlane32_swap_b32_e32 v10, v14
	v_permlane32_swap_b32_e32 v11, v15
	v_permlane32_swap_b32_e32 v12, v16
	v_permlane32_swap_b32_e32 v13, v17
	s_nop 1
	s_branch .LBB0_195

; DI int tid512() { int t = threadIdx.x; asm volatile("" : "+v"(t)); return t; }
; DI unsigned voff256(size_t ld) { const int t = tid512(); return (unsigned)(((size_t)(t >> 3) * ld + (t & 7) * 8) * 2); }
; DI void gemm256(const char* a_u, unsigned a_voff, size_t astep, const char* b_u, unsigned b_voff, size_t bstep, int nk, char* smem, f32x16 (&acc)[4][2]) {
;   asm volatile("" : "+s"(nk));
;   const int t = tid512(), lane = t & 63, w = t >> 6, wm = w >> 2, wn = w & 3, r = lane & 31, h = lane >> 5;
;   const int soff = (t >> 3) * LROW + (t & 7) * 16;
;   const int aoff = (128 * wm + r) * LROW + h * 16, boff = T2 + (64 * wn + r) * LROW + h * 16;
;   u32x4 ra[4], rb[4];
; #pragma unroll
;   for (int i = 0; i < 4; ++i) { ra[i] = *(const u32x4*)(a_u + i * astep + a_voff); rb[i] = *(const u32x4*)(b_u + i * bstep + b_voff); }
;   __syncthreads();
; #pragma unroll
;   for (int i = 0; i < 4; ++i) { *(u32x4*)(smem + soff + i * 64 * LROW) = ra[i]; *(u32x4*)(smem + T2 + soff + i * 64 * LROW) = rb[i]; }
;   const int last = nk - 1;
;   {
;     const int k1 = last < 1 ? last : 1;
; #pragma unroll
;     for (int i = 0; i < 4; ++i) { ra[i] = *(const u32x4*)(a_u + i * astep + k1 * 128 + a_voff); rb[i] = *(const u32x4*)(b_u + i * bstep + k1 * 128 + b_voff); }
;   }
;   __syncthreads();
; DI void outproj256(const Params& p, int layer, char* smem) {
;     ...
;   for (int i = 0;; ++i) {
;     const int L = tile_of(i, 32 * 8);
;     if (L < 0) break;
;     int tm, tn; tile_mn(L, 32, 8, tm, tn);
;     f32x16 acc[4][2]; zero_acc256(acc);
;     gemm256((const char*)(Yb + (size_t)(256 + tm * 256) * DM), voff256(DM), (size_t)128 * DM, (const char*)(W + (size_t)(tn * 256) * DM), voff256(DM), (size_t)128 * DM, DM / 64, smem, acc);
.LBB0_918:
	s_lshr_b32 s4, s6, 3
	s_and_b32 s5, s4, 0xffffffc
	s_sub_i32 s4, 32, s5
	s_min_i32 s7, s4, 4
	s_abs_i32 s8, s7
	v_cvt_f32_u32_e32 v2, s8
	s_sub_i32 s9, 0, s8
	s_and_b32 s6, s6, 31
	s_ashr_i32 s4, s7, 31
	v_rcp_iflag_f32_e32 v2, v2
	v_mov_b32_e32 v37, v181
	v_mul_f32_e32 v2, 0x4f7ffffe, v2
	v_cvt_u32_f32_e32 v2, v2
	s_nop 0
	v_readfirstlane_b32 s13, v2
	s_mul_i32 s9, s9, s13
	s_mul_hi_u32 s9, s13, s9
	s_add_i32 s13, s13, s9
	s_mul_hi_u32 s9, s6, s13
	s_mul_i32 s13, s9, s8
	s_sub_i32 s13, s6, s13
	s_add_i32 s14, s9, 1
	s_sub_i32 s15, s13, s8
	s_cmp_ge_u32 s13, s8
	s_cselect_b32 s9, s14, s9
	s_cselect_b32 s13, s15, s13
	s_add_i32 s14, s9, 1
	s_cmp_ge_u32 s13, s8
	s_cselect_b32 s8, s14, s9
	s_xor_b32 s8, s8, s4
	s_sub_i32 s4, s8, s4
	s_mul_i32 s7, s4, s7
	s_sub_i32 s6, s6, s7
	s_add_i32 s6, s6, s5
	s_lshl_b32 s5, s6, 8
	s_add_i32 s22, s5, 0x100
	s_lshl_b64 s[6:7], s[22:23], 12
	v_readlane_b32 s5, v254, 20
	v_mov_b32_e32 v2, v0
	s_add_u32 s6, s5, s6
	v_readlane_b32 s5, v254, 21
	s_addc_u32 s7, s5, s7
	v_lshlrev_b32_e32 v3, 4, v2
	v_and_b32_e32 v3, 0x70, v3
	v_lshlrev_b32_e32 v2, 9, v2
	s_movk_i32 s13, 0xf000
	s_lshl_b32 s4, s4, 8
	v_and_or_b32 v180, v2, s13, v3
	s_ashr_i32 s5, s4, 31
	v_mov_b32_e32 v2, v0
	s_lshl_b64 s[8:9], s[4:5], 12
	s_add_u32 s8, s10, s8
	v_lshlrev_b32_e32 v3, 4, v2
	v_and_b32_e32 v3, 0x70, v3
	v_lshlrev_b32_e32 v2, 9, v2
	v_lshl_add_u64 v[162:163], s[6:7], 0, v[180:181]
	s_addc_u32 s9, s11, s9
	v_and_or_b32 v36, v2, s13, v3
	v_add_co_u32_e32 v12, vcc, s84, v162
	v_lshl_add_u64 v[164:165], s[8:9], 0, v[36:37]
	s_nop 0
	v_addc_co_u32_e32 v13, vcc, 0, v163, vcc
	v_add_co_u32_e32 v16, vcc, s84, v164
	s_mov_b32 s5, 32
	v_mov_b32_e32 v2, v0
	v_addc_co_u32_e32 v17, vcc, 0, v165, vcc
	v_add_co_u32_e32 v20, vcc, s31, v162
	v_lshlrev_b32_e32 v4, 4, v2
	v_and_b32_e32 v38, 0x70, v4
	v_lshrrev_b32_e32 v132, 6, v0
	s_nop 0
	v_readfirstlane_b32 s61, v132
	v_and_b32_e32 v132, 63, v0
	v_and_b32_e32 v133, 15, v132
	v_lshrrev_b32_e32 v136, 4, v132
	v_bfe_u32 v137, v133, 1, 3
	v_lshlrev_b32_e32 v133, 7, v133
	s_lshr_b32 s60, s61, 2
	s_lshl_b32 s60, s60, 14
	s_add_i32 s60, s60, 16
	s_and_b32 s62, s61, 3
	s_lshl_b32 s62, s62, 13
	s_add_i32 s62, s62, 0x10010
	v_add_u32_e32 v194, 0, v136
	v_xor_b32_e32 v194, v194, v137
	v_lshl_add_u32 v194, v194, 4, v133
	v_add_u32_e32 v160, s62, v194
	v_add_u32_e32 v194, s60, v194
	v_add_u32_e32 v195, 4, v136
	v_xor_b32_e32 v195, v195, v137
	v_lshl_add_u32 v195, v195, 4, v133
	v_add_u32_e32 v161, s62, v195
	v_add_u32_e32 v195, s60, v195
	v_lshrrev_b32_e32 v133, 3, v132
	s_mov_b32 s60, 0x1000
	v_mul_lo_u32 v133, v133, s60
	v_and_b32_e32 v136, 7, v132
	v_lshrrev_b32_e32 v137, 4, v132
	v_xor_b32_e32 v164, v137, v136
	v_lshl_add_u32 v164, v164, 4, v133
	v_add_u32_e32 v165, 4, v137
	v_xor_b32_e32 v165, v165, v136
	v_lshl_add_u32 v165, v165, 4, v133
	v_add_u32_e32 v165, 0x7c00, v165
	v_xor_b32_e32 v130, v137, v136
	v_lshl_add_u32 v130, v130, 4, v133
	v_add_u32_e32 v130, 0xf800, v130
	v_add_u32_e32 v131, 4, v137
	v_xor_b32_e32 v131, v131, v136
	v_lshl_add_u32 v131, v131, 4, v133
	v_add_u32_e32 v131, 0x17400, v131
	s_mul_i32 s60, s61, 0x20000
	s_add_u32 s52, s6, s60
	s_addc_u32 s53, s7, 0
	s_add_u32 s54, s8, s60
	s_addc_u32 s55, s9, 0
	s_lshl_b32 s58, s61, 12
	s_add_i32 s58, s58, 16
	s_add_i32 s59, s58, 0x10000
	s_mov_b32 s56, 0
	s_mov_b32 s57, 31
	s_barrier
	s_add_u32 m0, s58, 0x0
	s_nop 0
	global_load_lds_dwordx4 v164, s[52:53]
	global_load_lds_dwordx4 v165, s[52:53] offset:1024
	global_load_lds_dwordx4 v130, s[52:53] offset:2048
	global_load_lds_dwordx4 v131, s[52:53] offset:3072
	s_add_u32 m0, s59, 0x0
	s_nop 0
	global_load_lds_dwordx4 v164, s[54:55]
	global_load_lds_dwordx4 v165, s[54:55] offset:1024
	global_load_lds_dwordx4 v130, s[54:55] offset:2048
	global_load_lds_dwordx4 v131, s[54:55] offset:3072
	s_cmp_lt_u32 s56, s57
	s_cselect_b32 s60, 0x80, 0
	s_add_u32 s52, s52, s60
	s_addc_u32 s53, s53, 0
	s_add_u32 s54, s54, s60
	s_addc_u32 s55, s55, 0
	v_mov_b64_e32 v[114:115], 0
	v_mov_b64_e32 v[116:117], 0
	v_mov_b64_e32 v[118:119], 0
	v_mov_b64_e32 v[120:121], 0
	v_mov_b64_e32 v[122:123], 0
	v_mov_b64_e32 v[124:125], 0
	v_mov_b64_e32 v[126:127], 0
	v_mov_b64_e32 v[128:129], 0
	v_mov_b64_e32 v[98:99], 0
	v_mov_b64_e32 v[100:101], 0
	v_mov_b64_e32 v[102:103], 0
	v_mov_b64_e32 v[104:105], 0
	v_mov_b64_e32 v[106:107], 0
	v_mov_b64_e32 v[108:109], 0
	v_mov_b64_e32 v[110:111], 0
	v_mov_b64_e32 v[112:113], 0
	v_mov_b64_e32 v[82:83], 0
	v_mov_b64_e32 v[84:85], 0
	v_mov_b64_e32 v[86:87], 0
	v_mov_b64_e32 v[88:89], 0
	v_mov_b64_e32 v[90:91], 0
	v_mov_b64_e32 v[92:93], 0
	v_mov_b64_e32 v[94:95], 0
	v_mov_b64_e32 v[96:97], 0
	v_mov_b64_e32 v[66:67], 0
	v_mov_b64_e32 v[68:69], 0
	v_mov_b64_e32 v[70:71], 0
	v_mov_b64_e32 v[72:73], 0
	v_mov_b64_e32 v[74:75], 0
	v_mov_b64_e32 v[76:77], 0
	v_mov_b64_e32 v[78:79], 0
	v_mov_b64_e32 v[80:81], 0
	v_mov_b64_e32 v[50:51], 0
	v_mov_b64_e32 v[52:53], 0
	v_mov_b64_e32 v[54:55], 0
	v_mov_b64_e32 v[56:57], 0
	v_mov_b64_e32 v[58:59], 0
	v_mov_b64_e32 v[60:61], 0
	v_mov_b64_e32 v[62:63], 0
	v_mov_b64_e32 v[64:65], 0
	v_mov_b64_e32 v[34:35], 0
	v_mov_b64_e32 v[36:37], 0
	v_mov_b64_e32 v[38:39], 0
	v_mov_b64_e32 v[40:41], 0
	v_mov_b64_e32 v[42:43], 0
	v_mov_b64_e32 v[44:45], 0
	v_mov_b64_e32 v[46:47], 0
	v_mov_b64_e32 v[48:49], 0
	v_mov_b64_e32 v[18:19], 0
	v_mov_b64_e32 v[20:21], 0
	v_mov_b64_e32 v[22:23], 0
	v_mov_b64_e32 v[24:25], 0
	v_mov_b64_e32 v[26:27], 0
	v_mov_b64_e32 v[28:29], 0
	v_mov_b64_e32 v[30:31], 0
	v_mov_b64_e32 v[32:33], 0
	v_mov_b64_e32 v[2:3], 0
	v_mov_b64_e32 v[4:5], 0
	v_mov_b64_e32 v[6:7], 0
	v_mov_b64_e32 v[8:9], 0
	v_mov_b64_e32 v[10:11], 0
	v_mov_b64_e32 v[12:13], 0
	v_mov_b64_e32 v[14:15], 0
	v_mov_b64_e32 v[16:17], 0
	s_waitcnt vmcnt(0)
	s_barrier
	ds_read_b128 v[196:199], v194 offset:0
	ds_read_b128 v[212:215], v160 offset:0
	ds_read_b128 v[216:219], v160 offset:2048
	ds_read_b128 v[242:245], v160 offset:4096
	ds_read_b128 v[246:249], v160 offset:6144
	ds_read_b128 v[200:203], v194 offset:4096
	ds_read_b128 v[204:207], v194 offset:8192
	ds_read_b128 v[208:211], v194 offset:12288
; #define MFMA32(a, b, c) __builtin_amdgcn_mfma_f32_32x32x16_bf16((a), (b), (c), 0, 0, 0)
; DI void gemm256(const char* a_u, unsigned a_voff, size_t astep, const char* b_u, unsigned b_voff, size_t bstep, int nk, char* smem, f32x16 (&acc)[4][2]) {
;     ...
;   for (int kt = 0; kt < nk; ++kt) {
;     const int cur = kt & 1, k2 = (kt + 2 < last) ? kt + 2 : last;
;     const char* S = smem + cur * 2 * T2;
;     char* D = smem + (cur ^ 1) * 2 * T2;
;     const char* an = a_u + (size_t)k2 * 128;
;     const char* bn = b_u + (size_t)k2 * 128;
; #pragma unroll
;     for (int s = 0; s < 4; ++s) {
;       bf16x8 a[4], b[2];
; #pragma unroll
;       for (int mi = 0; mi < 4; ++mi) a[mi] = *(const bf16x8*)(S + aoff + mi * 32 * LROW + s * 32);
; #pragma unroll
;       for (int ni = 0; ni < 2; ++ni) b[ni] = *(const bf16x8*)(S + boff + ni * 32 * LROW + s * 32);
;       *(u32x4*)(D + soff + s * 64 * LROW) = ra[s];
;       *(u32x4*)(D + T2 + soff + s * 64 * LROW) = rb[s];
;       ra[s] = *(const u32x4*)(an + s * astep + a_voff);
;       rb[s] = *(const u32x4*)(bn + s * bstep + b_voff);
; #pragma unroll
;       for (int mi = 0; mi < 4; ++mi)
; #pragma unroll
;         for (int ni = 0; ni < 2; ++ni) acc[mi][ni] = MFMA32(a[mi], b[ni], acc[mi][ni]);
;     }
;     __syncthreads();
;   }
.Lg_outproj_loop:
	s_add_i32 s56, s56, 1
	s_add_u32 m0, s59, 0x8000
	s_nop 0
	global_load_lds_dwordx4 v164, s[54:55]
	global_load_lds_dwordx4 v165, s[54:55] offset:1024
	global_load_lds_dwordx4 v130, s[54:55] offset:2048
	global_load_lds_dwordx4 v131, s[54:55] offset:3072
	s_waitcnt lgkmcnt(0)
	v_mfma_f32_16x16x32_bf16 v[114:117], v[196:199], v[212:215], v[114:117]
	ds_read_b128 v[220:223], v194 offset:2048
	v_mfma_f32_16x16x32_bf16 v[118:121], v[196:199], v[216:219], v[118:121]
	ds_read_b128 v[224:227], v194 offset:6144
	v_mfma_f32_16x16x32_bf16 v[98:101], v[196:199], v[242:245], v[98:101]
	ds_read_b128 v[228:231], v194 offset:10240
	v_mfma_f32_16x16x32_bf16 v[102:105], v[196:199], v[246:249], v[102:105]
	ds_read_b128 v[238:241], v194 offset:14336
	v_mfma_f32_16x16x32_bf16 v[82:85], v[200:203], v[212:215], v[82:85]
	v_mfma_f32_16x16x32_bf16 v[86:89], v[200:203], v[216:219], v[86:89]
	v_mfma_f32_16x16x32_bf16 v[66:69], v[200:203], v[242:245], v[66:69]
	v_mfma_f32_16x16x32_bf16 v[70:73], v[200:203], v[246:249], v[70:73]
	v_mfma_f32_16x16x32_bf16 v[50:53], v[204:207], v[212:215], v[50:53]
	v_mfma_f32_16x16x32_bf16 v[54:57], v[204:207], v[216:219], v[54:57]
	v_mfma_f32_16x16x32_bf16 v[34:37], v[204:207], v[242:245], v[34:37]
	v_mfma_f32_16x16x32_bf16 v[38:41], v[204:207], v[246:249], v[38:41]
	v_mfma_f32_16x16x32_bf16 v[18:21], v[208:211], v[212:215], v[18:21]
	v_mfma_f32_16x16x32_bf16 v[22:25], v[208:211], v[216:219], v[22:25]
	v_mfma_f32_16x16x32_bf16 v[2:5], v[208:211], v[242:245], v[2:5]
	v_mfma_f32_16x16x32_bf16 v[6:9], v[208:211], v[246:249], v[6:9]
	s_add_u32 m0, s58, 0x8000
	s_nop 0
	global_load_lds_dwordx4 v164, s[52:53]
	global_load_lds_dwordx4 v165, s[52:53] offset:1024
	global_load_lds_dwordx4 v130, s[52:53] offset:2048
	global_load_lds_dwordx4 v131, s[52:53] offset:3072
	s_waitcnt lgkmcnt(0)
	v_mfma_f32_16x16x32_bf16 v[122:125], v[220:223], v[212:215], v[122:125]
	ds_read_b128 v[196:199], v195 offset:0
	v_mfma_f32_16x16x32_bf16 v[126:129], v[220:223], v[216:219], v[126:129]
	ds_read_b128 v[140:143], v161 offset:0
	v_mfma_f32_16x16x32_bf16 v[106:109], v[220:223], v[242:245], v[106:109]
	ds_read_b128 v[144:147], v161 offset:2048
	v_mfma_f32_16x16x32_bf16 v[110:113], v[220:223], v[246:249], v[110:113]
	ds_read_b128 v[148:151], v161 offset:4096
	v_mfma_f32_16x16x32_bf16 v[90:93], v[224:227], v[212:215], v[90:93]
	ds_read_b128 v[152:155], v161 offset:6144
	v_mfma_f32_16x16x32_bf16 v[94:97], v[224:227], v[216:219], v[94:97]
	ds_read_b128 v[200:203], v195 offset:4096
	v_mfma_f32_16x16x32_bf16 v[74:77], v[224:227], v[242:245], v[74:77]
	ds_read_b128 v[204:207], v195 offset:8192
	v_mfma_f32_16x16x32_bf16 v[78:81], v[224:227], v[246:249], v[78:81]
	ds_read_b128 v[208:211], v195 offset:12288
	v_mfma_f32_16x16x32_bf16 v[58:61], v[228:231], v[212:215], v[58:61]
	v_mfma_f32_16x16x32_bf16 v[62:65], v[228:231], v[216:219], v[62:65]
	v_mfma_f32_16x16x32_bf16 v[42:45], v[228:231], v[242:245], v[42:45]
	v_mfma_f32_16x16x32_bf16 v[46:49], v[228:231], v[246:249], v[46:49]
	v_mfma_f32_16x16x32_bf16 v[26:29], v[238:241], v[212:215], v[26:29]
	v_mfma_f32_16x16x32_bf16 v[30:33], v[238:241], v[216:219], v[30:33]
	v_mfma_f32_16x16x32_bf16 v[10:13], v[238:241], v[242:245], v[10:13]
	v_mfma_f32_16x16x32_bf16 v[14:17], v[238:241], v[246:249], v[14:17]
	s_waitcnt lgkmcnt(0)
	v_mfma_f32_16x16x32_bf16 v[114:117], v[196:199], v[140:143], v[114:117]
	ds_read_b128 v[220:223], v195 offset:2048
	v_mfma_f32_16x16x32_bf16 v[118:121], v[196:199], v[144:147], v[118:121]
	ds_read_b128 v[224:227], v195 offset:6144
	v_mfma_f32_16x16x32_bf16 v[98:101], v[196:199], v[148:151], v[98:101]
	ds_read_b128 v[228:231], v195 offset:10240
	v_mfma_f32_16x16x32_bf16 v[102:105], v[196:199], v[152:155], v[102:105]
	ds_read_b128 v[238:241], v195 offset:14336
	v_mfma_f32_16x16x32_bf16 v[82:85], v[200:203], v[140:143], v[82:85]
	v_mfma_f32_16x16x32_bf16 v[86:89], v[200:203], v[144:147], v[86:89]
	v_mfma_f32_16x16x32_bf16 v[66:69], v[200:203], v[148:151], v[66:69]
	v_mfma_f32_16x16x32_bf16 v[70:73], v[200:203], v[152:155], v[70:73]
	v_mfma_f32_16x16x32_bf16 v[50:53], v[204:207], v[140:143], v[50:53]
	v_mfma_f32_16x16x32_bf16 v[54:57], v[204:207], v[144:147], v[54:57]
	s_cmp_lt_u32 s56, s57
	s_cselect_b32 s60, 0x80, 0
	s_add_u32 s52, s52, s60
	s_addc_u32 s53, s53, 0
	s_add_u32 s54, s54, s60
	s_addc_u32 s55, s55, 0
	v_mfma_f32_16x16x32_bf16 v[34:37], v[204:207], v[148:151], v[34:37]
	v_mfma_f32_16x16x32_bf16 v[38:41], v[204:207], v[152:155], v[38:41]
	v_mfma_f32_16x16x32_bf16 v[18:21], v[208:211], v[140:143], v[18:21]
	v_mfma_f32_16x16x32_bf16 v[22:25], v[208:211], v[144:147], v[22:25]
	v_mfma_f32_16x16x32_bf16 v[2:5], v[208:211], v[148:151], v[2:5]
	v_mfma_f32_16x16x32_bf16 v[6:9], v[208:211], v[152:155], v[6:9]
	s_waitcnt lgkmcnt(0)
	v_mfma_f32_16x16x32_bf16 v[122:125], v[220:223], v[140:143], v[122:125]
	v_mfma_f32_16x16x32_bf16 v[126:129], v[220:223], v[144:147], v[126:129]
	v_mfma_f32_16x16x32_bf16 v[106:109], v[220:223], v[148:151], v[106:109]
	v_mfma_f32_16x16x32_bf16 v[110:113], v[220:223], v[152:155], v[110:113]
	v_mfma_f32_16x16x32_bf16 v[90:93], v[224:227], v[140:143], v[90:93]
	v_mfma_f32_16x16x32_bf16 v[94:97], v[224:227], v[144:147], v[94:97]
	v_mfma_f32_16x16x32_bf16 v[74:77], v[224:227], v[148:151], v[74:77]
	v_mfma_f32_16x16x32_bf16 v[78:81], v[224:227], v[152:155], v[78:81]
	v_mfma_f32_16x16x32_bf16 v[58:61], v[228:231], v[140:143], v[58:61]
	v_mfma_f32_16x16x32_bf16 v[62:65], v[228:231], v[144:147], v[62:65]
	v_mfma_f32_16x16x32_bf16 v[42:45], v[228:231], v[148:151], v[42:45]
	v_mfma_f32_16x16x32_bf16 v[46:49], v[228:231], v[152:155], v[46:49]
	v_mfma_f32_16x16x32_bf16 v[26:29], v[238:241], v[140:143], v[26:29]
	v_mfma_f32_16x16x32_bf16 v[30:33], v[238:241], v[144:147], v[30:33]
	v_mfma_f32_16x16x32_bf16 v[10:13], v[238:241], v[148:151], v[10:13]
	v_mfma_f32_16x16x32_bf16 v[14:17], v[238:241], v[152:155], v[14:17]
	s_waitcnt vmcnt(0)
	s_barrier
; #define MFMA32(a, b, c) __builtin_amdgcn_mfma_f32_32x32x16_bf16((a), (b), (c), 0, 0, 0)
; DI void gemm256(const char* a_u, unsigned a_voff, size_t astep, const char* b_u, unsigned b_voff, size_t bstep, int nk, char* smem, f32x16 (&acc)[4][2]) {
;     ...
;   for (int kt = 0; kt < nk; ++kt) {
;     const int cur = kt & 1, k2 = (kt + 2 < last) ? kt + 2 : last;
;     const char* S = smem + cur * 2 * T2;
;     char* D = smem + (cur ^ 1) * 2 * T2;
;     const char* an = a_u + (size_t)k2 * 128;
;     const char* bn = b_u + (size_t)k2 * 128;
; #pragma unroll
;     for (int s = 0; s < 4; ++s) {
;       bf16x8 a[4], b[2];
; #pragma unroll
;       for (int mi = 0; mi < 4; ++mi) a[mi] = *(const bf16x8*)(S + aoff + mi * 32 * LROW + s * 32);
; #pragma unroll
;       for (int ni = 0; ni < 2; ++ni) b[ni] = *(const bf16x8*)(S + boff + ni * 32 * LROW + s * 32);
;       *(u32x4*)(D + soff + s * 64 * LROW) = ra[s];
;       *(u32x4*)(D + T2 + soff + s * 64 * LROW) = rb[s];
;       ra[s] = *(const u32x4*)(an + s * astep + a_voff);
;       rb[s] = *(const u32x4*)(bn + s * bstep + b_voff);
; #pragma unroll
;       for (int mi = 0; mi < 4; ++mi)
; #pragma unroll
;         for (int ni = 0; ni < 2; ++ni) acc[mi][ni] = MFMA32(a[mi], b[ni], acc[mi][ni]);
;     }
;     __syncthreads();
;   }
	ds_read_b128 v[196:199], v194 offset:32768
	ds_read_b128 v[212:215], v160 offset:32768
	ds_read_b128 v[216:219], v160 offset:34816
	ds_read_b128 v[242:245], v160 offset:36864
	ds_read_b128 v[246:249], v160 offset:38912
	ds_read_b128 v[200:203], v194 offset:36864
	ds_read_b128 v[204:207], v194 offset:40960
	ds_read_b128 v[208:211], v194 offset:45056
	s_add_i32 s56, s56, 1
	s_add_u32 m0, s59, 0x0
	s_nop 0
	global_load_lds_dwordx4 v164, s[54:55]
	global_load_lds_dwordx4 v165, s[54:55] offset:1024
	global_load_lds_dwordx4 v130, s[54:55] offset:2048
	global_load_lds_dwordx4 v131, s[54:55] offset:3072
	s_waitcnt lgkmcnt(0)
	v_mfma_f32_16x16x32_bf16 v[114:117], v[196:199], v[212:215], v[114:117]
	ds_read_b128 v[220:223], v194 offset:34816
	v_mfma_f32_16x16x32_bf16 v[118:121], v[196:199], v[216:219], v[118:121]
	ds_read_b128 v[224:227], v194 offset:38912
	v_mfma_f32_16x16x32_bf16 v[98:101], v[196:199], v[242:245], v[98:101]
	ds_read_b128 v[228:231], v194 offset:43008
	v_mfma_f32_16x16x32_bf16 v[102:105], v[196:199], v[246:249], v[102:105]
	ds_read_b128 v[238:241], v194 offset:47104
	v_mfma_f32_16x16x32_bf16 v[82:85], v[200:203], v[212:215], v[82:85]
	v_mfma_f32_16x16x32_bf16 v[86:89], v[200:203], v[216:219], v[86:89]
	v_mfma_f32_16x16x32_bf16 v[66:69], v[200:203], v[242:245], v[66:69]
	v_mfma_f32_16x16x32_bf16 v[70:73], v[200:203], v[246:249], v[70:73]
	v_mfma_f32_16x16x32_bf16 v[50:53], v[204:207], v[212:215], v[50:53]
	v_mfma_f32_16x16x32_bf16 v[54:57], v[204:207], v[216:219], v[54:57]
	v_mfma_f32_16x16x32_bf16 v[34:37], v[204:207], v[242:245], v[34:37]
	v_mfma_f32_16x16x32_bf16 v[38:41], v[204:207], v[246:249], v[38:41]
	v_mfma_f32_16x16x32_bf16 v[18:21], v[208:211], v[212:215], v[18:21]
	v_mfma_f32_16x16x32_bf16 v[22:25], v[208:211], v[216:219], v[22:25]
	v_mfma_f32_16x16x32_bf16 v[2:5], v[208:211], v[242:245], v[2:5]
	v_mfma_f32_16x16x32_bf16 v[6:9], v[208:211], v[246:249], v[6:9]
	s_add_u32 m0, s58, 0x0
	s_nop 0
	global_load_lds_dwordx4 v164, s[52:53]
	global_load_lds_dwordx4 v165, s[52:53] offset:1024
	global_load_lds_dwordx4 v130, s[52:53] offset:2048
	global_load_lds_dwordx4 v131, s[52:53] offset:3072
	s_waitcnt lgkmcnt(0)
	v_mfma_f32_16x16x32_bf16 v[122:125], v[220:223], v[212:215], v[122:125]
	ds_read_b128 v[196:199], v195 offset:32768
	v_mfma_f32_16x16x32_bf16 v[126:129], v[220:223], v[216:219], v[126:129]
	ds_read_b128 v[140:143], v161 offset:32768
	v_mfma_f32_16x16x32_bf16 v[106:109], v[220:223], v[242:245], v[106:109]
	ds_read_b128 v[144:147], v161 offset:34816
	v_mfma_f32_16x16x32_bf16 v[110:113], v[220:223], v[246:249], v[110:113]
	ds_read_b128 v[148:151], v161 offset:36864
	v_mfma_f32_16x16x32_bf16 v[90:93], v[224:227], v[212:215], v[90:93]
	ds_read_b128 v[152:155], v161 offset:38912
	v_mfma_f32_16x16x32_bf16 v[94:97], v[224:227], v[216:219], v[94:97]
	ds_read_b128 v[200:203], v195 offset:36864
	v_mfma_f32_16x16x32_bf16 v[74:77], v[224:227], v[242:245], v[74:77]
	ds_read_b128 v[204:207], v195 offset:40960
	v_mfma_f32_16x16x32_bf16 v[78:81], v[224:227], v[246:249], v[78:81]
	ds_read_b128 v[208:211], v195 offset:45056
	v_mfma_f32_16x16x32_bf16 v[58:61], v[228:231], v[212:215], v[58:61]
	v_mfma_f32_16x16x32_bf16 v[62:65], v[228:231], v[216:219], v[62:65]
	v_mfma_f32_16x16x32_bf16 v[42:45], v[228:231], v[242:245], v[42:45]
	v_mfma_f32_16x16x32_bf16 v[46:49], v[228:231], v[246:249], v[46:49]
	v_mfma_f32_16x16x32_bf16 v[26:29], v[238:241], v[212:215], v[26:29]
	v_mfma_f32_16x16x32_bf16 v[30:33], v[238:241], v[216:219], v[30:33]
	v_mfma_f32_16x16x32_bf16 v[10:13], v[238:241], v[242:245], v[10:13]
	v_mfma_f32_16x16x32_bf16 v[14:17], v[238:241], v[246:249], v[14:17]
	s_waitcnt lgkmcnt(0)
	v_mfma_f32_16x16x32_bf16 v[114:117], v[196:199], v[140:143], v[114:117]
	ds_read_b128 v[220:223], v195 offset:34816
	v_mfma_f32_16x16x32_bf16 v[118:121], v[196:199], v[144:147], v[118:121]
	ds_read_b128 v[224:227], v195 offset:38912
	v_mfma_f32_16x16x32_bf16 v[98:101], v[196:199], v[148:151], v[98:101]
	ds_read_b128 v[228:231], v195 offset:43008
	v_mfma_f32_16x16x32_bf16 v[102:105], v[196:199], v[152:155], v[102:105]
	ds_read_b128 v[238:241], v195 offset:47104
	v_mfma_f32_16x16x32_bf16 v[82:85], v[200:203], v[140:143], v[82:85]
	v_mfma_f32_16x16x32_bf16 v[86:89], v[200:203], v[144:147], v[86:89]
	v_mfma_f32_16x16x32_bf16 v[66:69], v[200:203], v[148:151], v[66:69]
	v_mfma_f32_16x16x32_bf16 v[70:73], v[200:203], v[152:155], v[70:73]
	v_mfma_f32_16x16x32_bf16 v[50:53], v[204:207], v[140:143], v[50:53]
	v_mfma_f32_16x16x32_bf16 v[54:57], v[204:207], v[144:147], v[54:57]
	s_cmp_lt_u32 s56, s57
	s_cselect_b32 s60, 0x80, 0
	s_add_u32 s52, s52, s60
	s_addc_u32 s53, s53, 0
	s_add_u32 s54, s54, s60
	s_addc_u32 s55, s55, 0
	v_mfma_f32_16x16x32_bf16 v[34:37], v[204:207], v[148:151], v[34:37]
	v_mfma_f32_16x16x32_bf16 v[38:41], v[204:207], v[152:155], v[38:41]
	v_mfma_f32_16x16x32_bf16 v[18:21], v[208:211], v[140:143], v[18:21]
	v_mfma_f32_16x16x32_bf16 v[22:25], v[208:211], v[144:147], v[22:25]
	v_mfma_f32_16x16x32_bf16 v[2:5], v[208:211], v[148:151], v[2:5]
	v_mfma_f32_16x16x32_bf16 v[6:9], v[208:211], v[152:155], v[6:9]
	s_waitcnt lgkmcnt(0)
	v_mfma_f32_16x16x32_bf16 v[122:125], v[220:223], v[140:143], v[122:125]
	v_mfma_f32_16x16x32_bf16 v[126:129], v[220:223], v[144:147], v[126:129]
	v_mfma_f32_16x16x32_bf16 v[106:109], v[220:223], v[148:151], v[106:109]
	v_mfma_f32_16x16x32_bf16 v[110:113], v[220:223], v[152:155], v[110:113]
	v_mfma_f32_16x16x32_bf16 v[90:93], v[224:227], v[140:143], v[90:93]
	v_mfma_f32_16x16x32_bf16 v[94:97], v[224:227], v[144:147], v[94:97]
	v_mfma_f32_16x16x32_bf16 v[74:77], v[224:227], v[148:151], v[74:77]
	v_mfma_f32_16x16x32_bf16 v[78:81], v[224:227], v[152:155], v[78:81]
	v_mfma_f32_16x16x32_bf16 v[58:61], v[228:231], v[140:143], v[58:61]
	v_mfma_f32_16x16x32_bf16 v[62:65], v[228:231], v[144:147], v[62:65]
	v_mfma_f32_16x16x32_bf16 v[42:45], v[228:231], v[148:151], v[42:45]
	v_mfma_f32_16x16x32_bf16 v[46:49], v[228:231], v[152:155], v[46:49]
	v_mfma_f32_16x16x32_bf16 v[26:29], v[238:241], v[140:143], v[26:29]
	v_mfma_f32_16x16x32_bf16 v[30:33], v[238:241], v[144:147], v[30:33]
	v_mfma_f32_16x16x32_bf16 v[10:13], v[238:241], v[148:151], v[10:13]
	v_mfma_f32_16x16x32_bf16 v[14:17], v[238:241], v[152:155], v[14:17]
	s_waitcnt vmcnt(0)
	s_barrier
; #define MFMA32(a, b, c) __builtin_amdgcn_mfma_f32_32x32x16_bf16((a), (b), (c), 0, 0, 0)
; DI void gemm256(const char* a_u, unsigned a_voff, size_t astep, const char* b_u, unsigned b_voff, size_t bstep, int nk, char* smem, f32x16 (&acc)[4][2]) {
;     ...
;   for (int kt = 0; kt < nk; ++kt) {
;     const int cur = kt & 1, k2 = (kt + 2 < last) ? kt + 2 : last;
;     const char* S = smem + cur * 2 * T2;
;     char* D = smem + (cur ^ 1) * 2 * T2;
;     const char* an = a_u + (size_t)k2 * 128;
;     const char* bn = b_u + (size_t)k2 * 128;
; #pragma unroll
;     for (int s = 0; s < 4; ++s) {
;       bf16x8 a[4], b[2];
; #pragma unroll
;       for (int mi = 0; mi < 4; ++mi) a[mi] = *(const bf16x8*)(S + aoff + mi * 32 * LROW + s * 32);
; #pragma unroll
;       for (int ni = 0; ni < 2; ++ni) b[ni] = *(const bf16x8*)(S + boff + ni * 32 * LROW + s * 32);
;       *(u32x4*)(D + soff + s * 64 * LROW) = ra[s];
;       *(u32x4*)(D + T2 + soff + s * 64 * LROW) = rb[s];
;       ra[s] = *(const u32x4*)(an + s * astep + a_voff);
;       rb[s] = *(const u32x4*)(bn + s * bstep + b_voff);
; #pragma unroll
;       for (int mi = 0; mi < 4; ++mi)
; #pragma unroll
;         for (int ni = 0; ni < 2; ++ni) acc[mi][ni] = MFMA32(a[mi], b[ni], acc[mi][ni]);
;     }
;     __syncthreads();
;   }
	ds_read_b128 v[196:199], v194 offset:0
	ds_read_b128 v[212:215], v160 offset:0
	ds_read_b128 v[216:219], v160 offset:2048
	ds_read_b128 v[242:245], v160 offset:4096
	ds_read_b128 v[246:249], v160 offset:6144
	ds_read_b128 v[200:203], v194 offset:4096
	ds_read_b128 v[204:207], v194 offset:8192
	ds_read_b128 v[208:211], v194 offset:12288
	s_cmp_lt_u32 s56, s57
	s_cbranch_scc1 .Lg_outproj_loop
	s_waitcnt vmcnt(0) lgkmcnt(0)
	s_nop 7
	s_nop 7
	v_permlane16_swap_b32_e32 v114, v118
	v_permlane16_swap_b32_e32 v115, v119
	v_permlane16_swap_b32_e32 v116, v120
	v_permlane16_swap_b32_e32 v117, v121
	v_permlane16_swap_b32_e32 v122, v126
	v_permlane16_swap_b32_e32 v123, v127
	v_permlane16_swap_b32_e32 v124, v128
	v_permlane16_swap_b32_e32 v125, v129
	v_permlane16_swap_b32_e32 v98, v102
	v_permlane16_swap_b32_e32 v99, v103
	v_permlane16_swap_b32_e32 v100, v104
	v_permlane16_swap_b32_e32 v101, v105
	v_permlane16_swap_b32_e32 v106, v110
	v_permlane16_swap_b32_e32 v107, v111
	v_permlane16_swap_b32_e32 v108, v112
	v_permlane16_swap_b32_e32 v109, v113
	v_permlane16_swap_b32_e32 v82, v86
	v_permlane16_swap_b32_e32 v83, v87
	v_permlane16_swap_b32_e32 v84, v88
	v_permlane16_swap_b32_e32 v85, v89
	v_permlane16_swap_b32_e32 v90, v94
	v_permlane16_swap_b32_e32 v91, v95
	v_permlane16_swap_b32_e32 v92, v96
	v_permlane16_swap_b32_e32 v93, v97
	v_permlane16_swap_b32_e32 v66, v70
	v_permlane16_swap_b32_e32 v67, v71
	v_permlane16_swap_b32_e32 v68, v72
	v_permlane16_swap_b32_e32 v69, v73
	v_permlane16_swap_b32_e32 v74, v78
	v_permlane16_swap_b32_e32 v75, v79
	v_permlane16_swap_b32_e32 v76, v80
	v_permlane16_swap_b32_e32 v77, v81
	v_permlane16_swap_b32_e32 v50, v54
	v_permlane16_swap_b32_e32 v51, v55
	v_permlane16_swap_b32_e32 v52, v56
	v_permlane16_swap_b32_e32 v53, v57
	v_permlane16_swap_b32_e32 v58, v62
	v_permlane16_swap_b32_e32 v59, v63
	v_permlane16_swap_b32_e32 v60, v64
	v_permlane16_swap_b32_e32 v61, v65
	v_permlane16_swap_b32_e32 v34, v38
	v_permlane16_swap_b32_e32 v35, v39
	v_permlane16_swap_b32_e32 v36, v40
	v_permlane16_swap_b32_e32 v37, v41
	v_permlane16_swap_b32_e32 v42, v46
	v_permlane16_swap_b32_e32 v43, v47
	v_permlane16_swap_b32_e32 v44, v48
	v_permlane16_swap_b32_e32 v45, v49
	v_permlane16_swap_b32_e32 v18, v22
	v_permlane16_swap_b32_e32 v19, v23
	v_permlane16_swap_b32_e32 v20, v24
	v_permlane16_swap_b32_e32 v21, v25
	v_permlane16_swap_b32_e32 v26, v30
	v_permlane16_swap_b32_e32 v27, v31
	v_permlane16_swap_b32_e32 v28, v32
	v_permlane16_swap_b32_e32 v29, v33
	v_permlane16_swap_b32_e32 v2, v6
	v_permlane16_swap_b32_e32 v3, v7
	v_permlane16_swap_b32_e32 v4, v8
	v_permlane16_swap_b32_e32 v5, v9
	v_permlane16_swap_b32_e32 v10, v14
	v_permlane16_swap_b32_e32 v11, v15
	v_permlane16_swap_b32_e32 v12, v16
	v_permlane16_swap_b32_e32 v13, v17
	v_permlane32_swap_b32_e32 v114, v118
	v_permlane32_swap_b32_e32 v115, v119
	v_permlane32_swap_b32_e32 v116, v120
	v_permlane32_swap_b32_e32 v117, v121
	v_permlane32_swap_b32_e32 v122, v126
	v_permlane32_swap_b32_e32 v123, v127
	v_permlane32_swap_b32_e32 v124, v128
	v_permlane32_swap_b32_e32 v125, v129
	v_permlane32_swap_b32_e32 v98, v102
	v_permlane32_swap_b32_e32 v99, v103
	v_permlane32_swap_b32_e32 v100, v104
	v_permlane32_swap_b32_e32 v101, v105
	v_permlane32_swap_b32_e32 v106, v110
	v_permlane32_swap_b32_e32 v107, v111
	v_permlane32_swap_b32_e32 v108, v112
	v_permlane32_swap_b32_e32 v109, v113
	v_permlane32_swap_b32_e32 v82, v86
	v_permlane32_swap_b32_e32 v83, v87
	v_permlane32_swap_b32_e32 v84, v88
	v_permlane32_swap_b32_e32 v85, v89
	v_permlane32_swap_b32_e32 v90, v94
	v_permlane32_swap_b32_e32 v91, v95
	v_permlane32_swap_b32_e32 v92, v96
	v_permlane32_swap_b32_e32 v93, v97
	v_permlane32_swap_b32_e32 v66, v70
	v_permlane32_swap_b32_e32 v67, v71
	v_permlane32_swap_b32_e32 v68, v72
	v_permlane32_swap_b32_e32 v69, v73
	v_permlane32_swap_b32_e32 v74, v78
	v_permlane32_swap_b32_e32 v75, v79
	v_permlane32_swap_b32_e32 v76, v80
	v_permlane32_swap_b32_e32 v77, v81
	v_permlane32_swap_b32_e32 v50, v54
	v_permlane32_swap_b32_e32 v51, v55
	v_permlane32_swap_b32_e32 v52, v56
	v_permlane32_swap_b32_e32 v53, v57
	v_permlane32_swap_b32_e32 v58, v62
	v_permlane32_swap_b32_e32 v59, v63
	v_permlane32_swap_b32_e32 v60, v64
	v_permlane32_swap_b32_e32 v61, v65
	v_permlane32_swap_b32_e32 v34, v38
	v_permlane32_swap_b32_e32 v35, v39
	v_permlane32_swap_b32_e32 v36, v40
	v_permlane32_swap_b32_e32 v37, v41
	v_permlane32_swap_b32_e32 v42, v46
	v_permlane32_swap_b32_e32 v43, v47
	v_permlane32_swap_b32_e32 v44, v48
	v_permlane32_swap_b32_e32 v45, v49
	v_permlane32_swap_b32_e32 v18, v22
	v_permlane32_swap_b32_e32 v19, v23
	v_permlane32_swap_b32_e32 v20, v24
	v_permlane32_swap_b32_e32 v21, v25
	v_permlane32_swap_b32_e32 v26, v30
	v_permlane32_swap_b32_e32 v27, v31
	v_permlane32_swap_b32_e32 v28, v32
	v_permlane32_swap_b32_e32 v29, v33
	v_permlane32_swap_b32_e32 v2, v6
	v_permlane32_swap_b32_e32 v3, v7
	v_permlane32_swap_b32_e32 v4, v8
	v_permlane32_swap_b32_e32 v5, v9
	v_permlane32_swap_b32_e32 v10, v14
	v_permlane32_swap_b32_e32 v11, v15
	v_permlane32_swap_b32_e32 v12, v16
	v_permlane32_swap_b32_e32 v13, v17
	s_nop 1
	s_branch .LBB0_925

; DI int tid512() { int t = threadIdx.x; asm volatile("" : "+v"(t)); return t; }
; DI unsigned voff256(size_t ld) { const int t = tid512(); return (unsigned)(((size_t)(t >> 3) * ld + (t & 7) * 8) * 2); }
; DI void gemm256(const char* a_u, unsigned a_voff, size_t astep, const char* b_u, unsigned b_voff, size_t bstep, int nk, char* smem, f32x16 (&acc)[4][2]) {
;   asm volatile("" : "+s"(nk));
;   const int t = tid512(), lane = t & 63, w = t >> 6, wm = w >> 2, wn = w & 3, r = lane & 31, h = lane >> 5;
;   const int soff = (t >> 3) * LROW + (t & 7) * 16;
;   const int aoff = (128 * wm + r) * LROW + h * 16, boff = T2 + (64 * wn + r) * LROW + h * 16;
;   u32x4 ra[4], rb[4];
; #pragma unroll
;   for (int i = 0; i < 4; ++i) { ra[i] = *(const u32x4*)(a_u + i * astep + a_voff); rb[i] = *(const u32x4*)(b_u + i * bstep + b_voff); }
;   __syncthreads();
; #pragma unroll
;   for (int i = 0; i < 4; ++i) { *(u32x4*)(smem + soff + i * 64 * LROW) = ra[i]; *(u32x4*)(smem + T2 + soff + i * 64 * LROW) = rb[i]; }
;   const int last = nk - 1;
;   {
;     const int k1 = last < 1 ? last : 1;
; #pragma unroll
;     for (int i = 0; i < 4; ++i) { ra[i] = *(const u32x4*)(a_u + i * astep + k1 * 128 + a_voff); rb[i] = *(const u32x4*)(b_u + i * bstep + k1 * 128 + b_voff); }
;   }
;   __syncthreads();
; DI void gateup256(const Params& p, int layer, char* smem) {
;     ...
;   for (int i = 0;; ++i) {
;     const int L = tile_of(i, 32 * 44);
;     if (L < 0) break;
;     int tm, nb; tile_mn(L, 32, 44, tm, nb);
;     const int t = tid512(), lane = t & 63, w = t >> 6, wm = w >> 2, wn = w & 3, r = lane & 31, h = lane >> 5;
;     const unsigned bvo = (unsigned)(((size_t)((t >> 3) & 31) * DM + (t & 7) * 8) * 2 + ((((t >> 3) >> 5) & 1) ? (O_WU - O_WG) : 0));
;     f32x16 acc[4][2]; zero_acc256(acc);
;     gemm256((const char*)(H + (size_t)(256 + tm * 256) * DM), voff256(DM), (size_t)128 * DM, (const char*)(WG + (size_t)(nb * 128) * DM), bvo, (size_t)64 * DM, DM / 64, smem, acc);
.LBB0_1564:
	s_mul_hi_u32 s4, s6, 0xba2e8ba3
	s_lshr_b32 s4, s4, 7
	s_lshl_b32 s5, s4, 2
	s_sub_i32 s7, 32, s5
	s_min_i32 s7, s7, 4
	s_abs_i32 s9, s7
	v_cvt_f32_u32_e32 v2, s9
	s_sub_i32 s10, 0, s9
	s_mulk_i32 s4, 0xff50
	s_add_i32 s4, s4, s6
	v_rcp_iflag_f32_e32 v2, v2
	s_abs_i32 s8, s4
	s_xor_b32 s6, s4, s7
	s_ashr_i32 s6, s6, 31
	v_mul_f32_e32 v2, 0x4f7ffffe, v2
	v_cvt_u32_f32_e32 v2, v2
	v_mov_b32_e32 v193, v0
	v_mov_b32_e32 v37, v181
	v_readfirstlane_b32 s11, v2
	s_mul_i32 s10, s10, s11
	s_mul_hi_u32 s10, s11, s10
	s_add_i32 s11, s11, s10
	s_mul_hi_u32 s10, s8, s11
	s_mul_i32 s11, s10, s9
	s_sub_i32 s8, s8, s11
	s_add_i32 s11, s10, 1
	s_sub_i32 s15, s8, s9
	s_cmp_ge_u32 s8, s9
	s_cselect_b32 s10, s11, s10
	s_cselect_b32 s8, s15, s8
	s_add_i32 s11, s10, 1
	s_cmp_ge_u32 s8, s9
	s_cselect_b32 s8, s11, s10
	s_xor_b32 s8, s8, s6
	s_sub_i32 s6, s8, s6
	s_mul_i32 s7, s6, s7
	s_sub_i32 s4, s4, s7
	s_add_i32 s4, s4, s5
	s_lshl_b32 s4, s4, 8
	s_addk_i32 s4, 0x100
	v_lshlrev_b32_e32 v2, 9, v193
	v_lshlrev_b32_e32 v3, 4, v193
	v_bfe_i32 v4, v193, 8, 1
	s_ashr_i32 s5, s4, 31
	v_and_b32_e32 v2, 0x1f000, v2
	v_and_b32_e32 v3, 0x70, v3
	v_and_b32_e32 v4, 0x2c00000, v4
	s_lshl_b64 s[8:9], s[4:5], 12
	v_or3_b32 v36, v2, v3, v4
	s_add_u32 s8, s92, s8
	v_mov_b32_e32 v2, v0
	s_addc_u32 s9, s93, s9
	s_lshl_b32 s6, s6, 7
	v_lshlrev_b32_e32 v3, 4, v2
	v_and_b32_e32 v3, 0x70, v3
	v_lshlrev_b32_e32 v2, 9, v2
	s_movk_i32 s5, 0xf000
	s_ashr_i32 s7, s6, 31
	v_and_or_b32 v180, v2, s5, v3
	s_lshl_b64 s[10:11], s[6:7], 12
	s_add_u32 s10, s12, s10
	v_lshl_add_u64 v[162:163], s[8:9], 0, v[180:181]
	s_addc_u32 s11, s13, s11
	v_add_co_u32_e32 v12, vcc, s84, v162
	v_lshl_add_u64 v[164:165], s[10:11], 0, v[36:37]
	s_nop 0
	v_addc_co_u32_e32 v13, vcc, 0, v163, vcc
	v_add_co_u32_e32 v16, vcc, s87, v164
	s_mov_b32 s5, 32
	v_mov_b32_e32 v2, v0
	v_addc_co_u32_e32 v17, vcc, 0, v165, vcc
	v_add_co_u32_e32 v20, vcc, s31, v162
	v_lshlrev_b32_e32 v4, 4, v2
	v_and_b32_e32 v38, 0x70, v4
	v_lshrrev_b32_e32 v132, 6, v0
	s_nop 0
	v_readfirstlane_b32 s61, v132
	v_and_b32_e32 v132, 63, v0
	v_and_b32_e32 v133, 15, v132
	v_lshrrev_b32_e32 v136, 4, v132
	v_bfe_u32 v137, v133, 1, 3
	v_lshlrev_b32_e32 v133, 7, v133
	s_lshr_b32 s60, s61, 2
	s_lshl_b32 s60, s60, 14
	s_add_i32 s60, s60, 16
	s_and_b32 s62, s61, 3
	s_lshl_b32 s62, s62, 13
	s_add_i32 s62, s62, 0x10010
	v_add_u32_e32 v194, 0, v136
	v_xor_b32_e32 v194, v194, v137
	v_lshl_add_u32 v194, v194, 4, v133
	v_add_u32_e32 v160, s62, v194
	v_add_u32_e32 v194, s60, v194
	v_add_u32_e32 v195, 4, v136
	v_xor_b32_e32 v195, v195, v137
	v_lshl_add_u32 v195, v195, 4, v133
	v_add_u32_e32 v161, s62, v195
	v_add_u32_e32 v195, s60, v195
	v_lshrrev_b32_e32 v133, 3, v132
	s_mov_b32 s60, 0x1000
	v_mul_lo_u32 v133, v133, s60
	v_and_b32_e32 v136, 7, v132
	v_lshrrev_b32_e32 v137, 4, v132
	v_xor_b32_e32 v164, v137, v136
	v_lshl_add_u32 v164, v164, 4, v133
	v_add_u32_e32 v165, 4, v137
	v_xor_b32_e32 v165, v165, v136
	v_lshl_add_u32 v165, v165, 4, v133
	v_add_u32_e32 v165, 0x7c00, v165
	v_xor_b32_e32 v130, v137, v136
	v_lshl_add_u32 v130, v130, 4, v133
	v_add_u32_e32 v130, 0xf800, v130
	v_add_u32_e32 v131, 4, v137
	v_xor_b32_e32 v131, v131, v136
	v_lshl_add_u32 v131, v131, 4, v133
	v_add_u32_e32 v131, 0x17400, v131
	s_mul_i32 s60, s61, 0x20000
	s_add_u32 s52, s8, s60
	s_addc_u32 s53, s9, 0
	s_lshr_b32 s60, s61, 1
	s_mul_i32 s60, s60, 0x20000
	s_and_b32 s62, s61, 1
	s_mul_i32 s62, s62, 0x2c00000
	s_add_u32 s60, s60, s62
	s_add_u32 s54, s10, s60
	s_addc_u32 s55, s11, 0
	s_lshl_b32 s58, s61, 12
	s_add_i32 s58, s58, 16
	s_add_i32 s59, s58, 0x10000
	s_mov_b32 s56, 0
	s_mov_b32 s57, 31
	s_add_u32 s64, s52, 0x0
	s_addc_u32 s65, s53, 0
	s_add_u32 s66, s54, 0x400000
	s_addc_u32 s67, s55, 0
	s_and_b64 s[62:63], exec, s[40:41]
	s_cselect_b32 s62, 0, 1
	s_add_i32 s60, s14, 1
	s_mul_i32 s60, s60, s88
	s_add_i32 s60, s60, s33
	s_cmp_lt_u32 s60, 176
	s_cselect_b32 s63, s57, -1
	s_cmp_eq_u32 s62, 1
	s_cselect_b32 s63, -1, s63
	s_cbranch_scc1 .Lg_gateup_first
	s_cmp_eq_u32 s14, 0
	s_cbranch_scc1 .Lg_gateup_first
	s_cmp_lt_u32 s56, s57
	s_cselect_b32 s60, 0x80, 0
	s_add_u32 s52, s52, s60
	s_addc_u32 s53, s53, 0
	s_add_u32 s54, s54, s60
	s_addc_u32 s55, s55, 0
	s_cmp_eq_u32 s56, s63
	s_cselect_b32 s52, s64, s52
	s_cselect_b32 s53, s65, s53
	s_cselect_b32 s54, s66, s54
	s_cselect_b32 s55, s67, s55
	v_mov_b64_e32 v[114:115], 0
	v_mov_b64_e32 v[116:117], 0
	v_mov_b64_e32 v[118:119], 0
	v_mov_b64_e32 v[120:121], 0
	v_mov_b64_e32 v[122:123], 0
	v_mov_b64_e32 v[124:125], 0
	v_mov_b64_e32 v[126:127], 0
	v_mov_b64_e32 v[128:129], 0
	v_mov_b64_e32 v[98:99], 0
	v_mov_b64_e32 v[100:101], 0
	v_mov_b64_e32 v[102:103], 0
	v_mov_b64_e32 v[104:105], 0
	v_mov_b64_e32 v[106:107], 0
	v_mov_b64_e32 v[108:109], 0
	v_mov_b64_e32 v[110:111], 0
	v_mov_b64_e32 v[112:113], 0
	v_mov_b64_e32 v[82:83], 0
	v_mov_b64_e32 v[84:85], 0
	v_mov_b64_e32 v[86:87], 0
	v_mov_b64_e32 v[88:89], 0
	v_mov_b64_e32 v[90:91], 0
	v_mov_b64_e32 v[92:93], 0
	v_mov_b64_e32 v[94:95], 0
	v_mov_b64_e32 v[96:97], 0
	v_mov_b64_e32 v[66:67], 0
	v_mov_b64_e32 v[68:69], 0
	v_mov_b64_e32 v[70:71], 0
	v_mov_b64_e32 v[72:73], 0
	v_mov_b64_e32 v[74:75], 0
	v_mov_b64_e32 v[76:77], 0
	v_mov_b64_e32 v[78:79], 0
	v_mov_b64_e32 v[80:81], 0
	v_mov_b64_e32 v[50:51], 0
	v_mov_b64_e32 v[52:53], 0
	v_mov_b64_e32 v[54:55], 0
	v_mov_b64_e32 v[56:57], 0
	v_mov_b64_e32 v[58:59], 0
	v_mov_b64_e32 v[60:61], 0
	v_mov_b64_e32 v[62:63], 0
	v_mov_b64_e32 v[64:65], 0
	v_mov_b64_e32 v[34:35], 0
	v_mov_b64_e32 v[36:37], 0
	v_mov_b64_e32 v[38:39], 0
	v_mov_b64_e32 v[40:41], 0
	v_mov_b64_e32 v[42:43], 0
	v_mov_b64_e32 v[44:45], 0
	v_mov_b64_e32 v[46:47], 0
	v_mov_b64_e32 v[48:49], 0
	v_mov_b64_e32 v[18:19], 0
	v_mov_b64_e32 v[20:21], 0
	v_mov_b64_e32 v[22:23], 0
	v_mov_b64_e32 v[24:25], 0
	v_mov_b64_e32 v[26:27], 0
	v_mov_b64_e32 v[28:29], 0
	v_mov_b64_e32 v[30:31], 0
	v_mov_b64_e32 v[32:33], 0
	v_mov_b64_e32 v[2:3], 0
	v_mov_b64_e32 v[4:5], 0
	v_mov_b64_e32 v[6:7], 0
	v_mov_b64_e32 v[8:9], 0
	v_mov_b64_e32 v[10:11], 0
	v_mov_b64_e32 v[12:13], 0
	v_mov_b64_e32 v[14:15], 0
	v_mov_b64_e32 v[16:17], 0
	s_branch .Lg_gateup_go
; DI int tid512() { int t = threadIdx.x; asm volatile("" : "+v"(t)); return t; }
; DI void gemm256(const char* a_u, unsigned a_voff, size_t astep, const char* b_u, unsigned b_voff, size_t bstep, int nk, char* smem, f32x16 (&acc)[4][2]) {
;   asm volatile("" : "+s"(nk));
;   const int t = tid512(), lane = t & 63, w = t >> 6, wm = w >> 2, wn = w & 3, r = lane & 31, h = lane >> 5;
;   const int soff = (t >> 3) * LROW + (t & 7) * 16;
;   const int aoff = (128 * wm + r) * LROW + h * 16, boff = T2 + (64 * wn + r) * LROW + h * 16;
;   u32x4 ra[4], rb[4];
; #pragma unroll
;   for (int i = 0; i < 4; ++i) { ra[i] = *(const u32x4*)(a_u + i * astep + a_voff); rb[i] = *(const u32x4*)(b_u + i * bstep + b_voff); }
;   __syncthreads();
; #pragma unroll
;   for (int i = 0; i < 4; ++i) { *(u32x4*)(smem + soff + i * 64 * LROW) = ra[i]; *(u32x4*)(smem + T2 + soff + i * 64 * LROW) = rb[i]; }
;   const int last = nk - 1;
;   {
;     const int k1 = last < 1 ? last : 1;
; #pragma unroll
;     for (int i = 0; i < 4; ++i) { ra[i] = *(const u32x4*)(a_u + i * astep + k1 * 128 + a_voff); rb[i] = *(const u32x4*)(b_u + i * bstep + k1 * 128 + b_voff); }
;   }
;   __syncthreads();
.Lg_gateup_first:
	s_barrier
	s_add_u32 m0, s58, 0x0
	s_nop 0
	global_load_lds_dwordx4 v164, s[52:53]
	global_load_lds_dwordx4 v165, s[52:53] offset:1024
	global_load_lds_dwordx4 v130, s[52:53] offset:2048
	global_load_lds_dwordx4 v131, s[52:53] offset:3072
	s_add_u32 m0, s59, 0x0
	s_nop 0
	global_load_lds_dwordx4 v164, s[54:55]
	global_load_lds_dwordx4 v165, s[54:55] offset:1024
	global_load_lds_dwordx4 v130, s[54:55] offset:2048
	global_load_lds_dwordx4 v131, s[54:55] offset:3072
	s_cmp_lt_u32 s56, s57
	s_cselect_b32 s60, 0x80, 0
	s_add_u32 s52, s52, s60
	s_addc_u32 s53, s53, 0
	s_add_u32 s54, s54, s60
	s_addc_u32 s55, s55, 0
	s_cmp_eq_u32 s56, s63
	s_cselect_b32 s52, s64, s52
	s_cselect_b32 s53, s65, s53
	s_cselect_b32 s54, s66, s54
	s_cselect_b32 s55, s67, s55
	v_mov_b64_e32 v[114:115], 0
	v_mov_b64_e32 v[116:117], 0
	v_mov_b64_e32 v[118:119], 0
	v_mov_b64_e32 v[120:121], 0
	v_mov_b64_e32 v[122:123], 0
	v_mov_b64_e32 v[124:125], 0
	v_mov_b64_e32 v[126:127], 0
	v_mov_b64_e32 v[128:129], 0
	v_mov_b64_e32 v[98:99], 0
	v_mov_b64_e32 v[100:101], 0
	v_mov_b64_e32 v[102:103], 0
	v_mov_b64_e32 v[104:105], 0
	v_mov_b64_e32 v[106:107], 0
	v_mov_b64_e32 v[108:109], 0
	v_mov_b64_e32 v[110:111], 0
	v_mov_b64_e32 v[112:113], 0
	v_mov_b64_e32 v[82:83], 0
	v_mov_b64_e32 v[84:85], 0
	v_mov_b64_e32 v[86:87], 0
	v_mov_b64_e32 v[88:89], 0
	v_mov_b64_e32 v[90:91], 0
	v_mov_b64_e32 v[92:93], 0
	v_mov_b64_e32 v[94:95], 0
	v_mov_b64_e32 v[96:97], 0
	v_mov_b64_e32 v[66:67], 0
	v_mov_b64_e32 v[68:69], 0
	v_mov_b64_e32 v[70:71], 0
	v_mov_b64_e32 v[72:73], 0
	v_mov_b64_e32 v[74:75], 0
	v_mov_b64_e32 v[76:77], 0
	v_mov_b64_e32 v[78:79], 0
	v_mov_b64_e32 v[80:81], 0
	v_mov_b64_e32 v[50:51], 0
	v_mov_b64_e32 v[52:53], 0
	v_mov_b64_e32 v[54:55], 0
	v_mov_b64_e32 v[56:57], 0
	v_mov_b64_e32 v[58:59], 0
	v_mov_b64_e32 v[60:61], 0
	v_mov_b64_e32 v[62:63], 0
	v_mov_b64_e32 v[64:65], 0
	v_mov_b64_e32 v[34:35], 0
	v_mov_b64_e32 v[36:37], 0
	v_mov_b64_e32 v[38:39], 0
	v_mov_b64_e32 v[40:41], 0
	v_mov_b64_e32 v[42:43], 0
	v_mov_b64_e32 v[44:45], 0
	v_mov_b64_e32 v[46:47], 0
	v_mov_b64_e32 v[48:49], 0
	v_mov_b64_e32 v[18:19], 0
	v_mov_b64_e32 v[20:21], 0
	v_mov_b64_e32 v[22:23], 0
	v_mov_b64_e32 v[24:25], 0
	v_mov_b64_e32 v[26:27], 0
	v_mov_b64_e32 v[28:29], 0
	v_mov_b64_e32 v[30:31], 0
	v_mov_b64_e32 v[32:33], 0
	v_mov_b64_e32 v[2:3], 0
	v_mov_b64_e32 v[4:5], 0
	v_mov_b64_e32 v[6:7], 0
	v_mov_b64_e32 v[8:9], 0
	v_mov_b64_e32 v[10:11], 0
	v_mov_b64_e32 v[12:13], 0
	v_mov_b64_e32 v[14:15], 0
	v_mov_b64_e32 v[16:17], 0
	s_waitcnt vmcnt(0)
	s_barrier

; #define MFMA32(a, b, c) __builtin_amdgcn_mfma_f32_32x32x16_bf16((a), (b), (c), 0, 0, 0)
; DI void gemm256(const char* a_u, unsigned a_voff, size_t astep, const char* b_u, unsigned b_voff, size_t bstep, int nk, char* smem, f32x16 (&acc)[4][2]) {
;     ...
;   for (int kt = 0; kt < nk; ++kt) {
;     const int cur = kt & 1, k2 = (kt + 2 < last) ? kt + 2 : last;
;     const char* S = smem + cur * 2 * T2;
;     char* D = smem + (cur ^ 1) * 2 * T2;
;     const char* an = a_u + (size_t)k2 * 128;
;     const char* bn = b_u + (size_t)k2 * 128;
; #pragma unroll
;     for (int s = 0; s < 4; ++s) {
;       bf16x8 a[4], b[2];
; #pragma unroll
;       for (int mi = 0; mi < 4; ++mi) a[mi] = *(const bf16x8*)(S + aoff + mi * 32 * LROW + s * 32);
; #pragma unroll
;       for (int ni = 0; ni < 2; ++ni) b[ni] = *(const bf16x8*)(S + boff + ni * 32 * LROW + s * 32);
;       *(u32x4*)(D + soff + s * 64 * LROW) = ra[s];
;       *(u32x4*)(D + T2 + soff + s * 64 * LROW) = rb[s];
;       ra[s] = *(const u32x4*)(an + s * astep + a_voff);
;       rb[s] = *(const u32x4*)(bn + s * bstep + b_voff);
; #pragma unroll
;       for (int mi = 0; mi < 4; ++mi)
; #pragma unroll
;         for (int ni = 0; ni < 2; ++ni) acc[mi][ni] = MFMA32(a[mi], b[ni], acc[mi][ni]);
;     }
;     __syncthreads();
;   }
.Lg_gateup_loop:
	s_add_i32 s56, s56, 1
	s_add_u32 m0, s59, 0x8000
	s_nop 0
	global_load_lds_dwordx4 v164, s[54:55]
	global_load_lds_dwordx4 v165, s[54:55] offset:1024
	global_load_lds_dwordx4 v130, s[54:55] offset:2048
	global_load_lds_dwordx4 v131, s[54:55] offset:3072
	s_waitcnt lgkmcnt(0)
	v_mfma_f32_16x16x32_bf16 v[114:117], v[196:199], v[212:215], v[114:117]
	ds_read_b128 v[220:223], v194 offset:2048
	v_mfma_f32_16x16x32_bf16 v[118:121], v[196:199], v[216:219], v[118:121]
	ds_read_b128 v[224:227], v194 offset:6144
	v_mfma_f32_16x16x32_bf16 v[98:101], v[196:199], v[242:245], v[98:101]
	ds_read_b128 v[228:231], v194 offset:10240
	v_mfma_f32_16x16x32_bf16 v[102:105], v[196:199], v[246:249], v[102:105]
	ds_read_b128 v[238:241], v194 offset:14336
	v_mfma_f32_16x16x32_bf16 v[82:85], v[200:203], v[212:215], v[82:85]
	v_mfma_f32_16x16x32_bf16 v[86:89], v[200:203], v[216:219], v[86:89]
	v_mfma_f32_16x16x32_bf16 v[66:69], v[200:203], v[242:245], v[66:69]
	v_mfma_f32_16x16x32_bf16 v[70:73], v[200:203], v[246:249], v[70:73]
	v_mfma_f32_16x16x32_bf16 v[50:53], v[204:207], v[212:215], v[50:53]
	v_mfma_f32_16x16x32_bf16 v[54:57], v[204:207], v[216:219], v[54:57]
	v_mfma_f32_16x16x32_bf16 v[34:37], v[204:207], v[242:245], v[34:37]
	v_mfma_f32_16x16x32_bf16 v[38:41], v[204:207], v[246:249], v[38:41]
	v_mfma_f32_16x16x32_bf16 v[18:21], v[208:211], v[212:215], v[18:21]
	v_mfma_f32_16x16x32_bf16 v[22:25], v[208:211], v[216:219], v[22:25]
	v_mfma_f32_16x16x32_bf16 v[2:5], v[208:211], v[242:245], v[2:5]
	v_mfma_f32_16x16x32_bf16 v[6:9], v[208:211], v[246:249], v[6:9]
	s_add_u32 m0, s58, 0x8000
	s_nop 0
	global_load_lds_dwordx4 v164, s[52:53]
	global_load_lds_dwordx4 v165, s[52:53] offset:1024
	global_load_lds_dwordx4 v130, s[52:53] offset:2048
	global_load_lds_dwordx4 v131, s[52:53] offset:3072
	s_waitcnt lgkmcnt(0)
	v_mfma_f32_16x16x32_bf16 v[122:125], v[220:223], v[212:215], v[122:125]
	ds_read_b128 v[196:199], v195 offset:0
	v_mfma_f32_16x16x32_bf16 v[126:129], v[220:223], v[216:219], v[126:129]
	ds_read_b128 v[140:143], v161 offset:0
	v_mfma_f32_16x16x32_bf16 v[106:109], v[220:223], v[242:245], v[106:109]
	ds_read_b128 v[144:147], v161 offset:2048
	v_mfma_f32_16x16x32_bf16 v[110:113], v[220:223], v[246:249], v[110:113]
	ds_read_b128 v[148:151], v161 offset:4096
	v_mfma_f32_16x16x32_bf16 v[90:93], v[224:227], v[212:215], v[90:93]
	ds_read_b128 v[152:155], v161 offset:6144
	v_mfma_f32_16x16x32_bf16 v[94:97], v[224:227], v[216:219], v[94:97]
	ds_read_b128 v[200:203], v195 offset:4096
	v_mfma_f32_16x16x32_bf16 v[74:77], v[224:227], v[242:245], v[74:77]
	ds_read_b128 v[204:207], v195 offset:8192
	v_mfma_f32_16x16x32_bf16 v[78:81], v[224:227], v[246:249], v[78:81]
	ds_read_b128 v[208:211], v195 offset:12288
	v_mfma_f32_16x16x32_bf16 v[58:61], v[228:231], v[212:215], v[58:61]
	v_mfma_f32_16x16x32_bf16 v[62:65], v[228:231], v[216:219], v[62:65]
	v_mfma_f32_16x16x32_bf16 v[42:45], v[228:231], v[242:245], v[42:45]
	v_mfma_f32_16x16x32_bf16 v[46:49], v[228:231], v[246:249], v[46:49]
	v_mfma_f32_16x16x32_bf16 v[26:29], v[238:241], v[212:215], v[26:29]
	v_mfma_f32_16x16x32_bf16 v[30:33], v[238:241], v[216:219], v[30:33]
	v_mfma_f32_16x16x32_bf16 v[10:13], v[238:241], v[242:245], v[10:13]
	v_mfma_f32_16x16x32_bf16 v[14:17], v[238:241], v[246:249], v[14:17]
	s_waitcnt lgkmcnt(0)
	v_mfma_f32_16x16x32_bf16 v[114:117], v[196:199], v[140:143], v[114:117]
	ds_read_b128 v[220:223], v195 offset:2048
	v_mfma_f32_16x16x32_bf16 v[118:121], v[196:199], v[144:147], v[118:121]
	ds_read_b128 v[224:227], v195 offset:6144
	v_mfma_f32_16x16x32_bf16 v[98:101], v[196:199], v[148:151], v[98:101]
	ds_read_b128 v[228:231], v195 offset:10240
	v_mfma_f32_16x16x32_bf16 v[102:105], v[196:199], v[152:155], v[102:105]
	ds_read_b128 v[238:241], v195 offset:14336
	v_mfma_f32_16x16x32_bf16 v[82:85], v[200:203], v[140:143], v[82:85]
	v_mfma_f32_16x16x32_bf16 v[86:89], v[200:203], v[144:147], v[86:89]
	v_mfma_f32_16x16x32_bf16 v[66:69], v[200:203], v[148:151], v[66:69]
	v_mfma_f32_16x16x32_bf16 v[70:73], v[200:203], v[152:155], v[70:73]
	v_mfma_f32_16x16x32_bf16 v[50:53], v[204:207], v[140:143], v[50:53]
	v_mfma_f32_16x16x32_bf16 v[54:57], v[204:207], v[144:147], v[54:57]
	s_cmp_lt_u32 s56, s57
	s_cselect_b32 s60, 0x80, 0
	s_add_u32 s52, s52, s60
	s_addc_u32 s53, s53, 0
	s_add_u32 s54, s54, s60
	s_addc_u32 s55, s55, 0
	s_cmp_eq_u32 s56, s63
	s_cselect_b32 s52, s64, s52
	s_cselect_b32 s53, s65, s53
	s_cselect_b32 s54, s66, s54
	s_cselect_b32 s55, s67, s55
	v_mfma_f32_16x16x32_bf16 v[34:37], v[204:207], v[148:151], v[34:37]
	v_mfma_f32_16x16x32_bf16 v[38:41], v[204:207], v[152:155], v[38:41]
	v_mfma_f32_16x16x32_bf16 v[18:21], v[208:211], v[140:143], v[18:21]
	v_mfma_f32_16x16x32_bf16 v[22:25], v[208:211], v[144:147], v[22:25]
	v_mfma_f32_16x16x32_bf16 v[2:5], v[208:211], v[148:151], v[2:5]
	v_mfma_f32_16x16x32_bf16 v[6:9], v[208:211], v[152:155], v[6:9]
	s_waitcnt lgkmcnt(0)
	v_mfma_f32_16x16x32_bf16 v[122:125], v[220:223], v[140:143], v[122:125]
	v_mfma_f32_16x16x32_bf16 v[126:129], v[220:223], v[144:147], v[126:129]
	v_mfma_f32_16x16x32_bf16 v[106:109], v[220:223], v[148:151], v[106:109]
	v_mfma_f32_16x16x32_bf16 v[110:113], v[220:223], v[152:155], v[110:113]
	v_mfma_f32_16x16x32_bf16 v[90:93], v[224:227], v[140:143], v[90:93]
	v_mfma_f32_16x16x32_bf16 v[94:97], v[224:227], v[144:147], v[94:97]
	v_mfma_f32_16x16x32_bf16 v[74:77], v[224:227], v[148:151], v[74:77]
	v_mfma_f32_16x16x32_bf16 v[78:81], v[224:227], v[152:155], v[78:81]
	v_mfma_f32_16x16x32_bf16 v[58:61], v[228:231], v[140:143], v[58:61]
	v_mfma_f32_16x16x32_bf16 v[62:65], v[228:231], v[144:147], v[62:65]
	v_mfma_f32_16x16x32_bf16 v[42:45], v[228:231], v[148:151], v[42:45]
	v_mfma_f32_16x16x32_bf16 v[46:49], v[228:231], v[152:155], v[46:49]
	v_mfma_f32_16x16x32_bf16 v[26:29], v[238:241], v[140:143], v[26:29]
	v_mfma_f32_16x16x32_bf16 v[30:33], v[238:241], v[144:147], v[30:33]
	v_mfma_f32_16x16x32_bf16 v[10:13], v[238:241], v[148:151], v[10:13]
	v_mfma_f32_16x16x32_bf16 v[14:17], v[238:241], v[152:155], v[14:17]
	s_waitcnt vmcnt(0)
	s_barrier
; #define MFMA32(a, b, c) __builtin_amdgcn_mfma_f32_32x32x16_bf16((a), (b), (c), 0, 0, 0)
; DI void gemm256(const char* a_u, unsigned a_voff, size_t astep, const char* b_u, unsigned b_voff, size_t bstep, int nk, char* smem, f32x16 (&acc)[4][2]) {
;     ...
;   for (int kt = 0; kt < nk; ++kt) {
;     const int cur = kt & 1, k2 = (kt + 2 < last) ? kt + 2 : last;
;     const char* S = smem + cur * 2 * T2;
;     char* D = smem + (cur ^ 1) * 2 * T2;
;     const char* an = a_u + (size_t)k2 * 128;
;     const char* bn = b_u + (size_t)k2 * 128;
; #pragma unroll
;     for (int s = 0; s < 4; ++s) {
;       bf16x8 a[4], b[2];
; #pragma unroll
;       for (int mi = 0; mi < 4; ++mi) a[mi] = *(const bf16x8*)(S + aoff + mi * 32 * LROW + s * 32);
; #pragma unroll
;       for (int ni = 0; ni < 2; ++ni) b[ni] = *(const bf16x8*)(S + boff + ni * 32 * LROW + s * 32);
;       *(u32x4*)(D + soff + s * 64 * LROW) = ra[s];
;       *(u32x4*)(D + T2 + soff + s * 64 * LROW) = rb[s];
;       ra[s] = *(const u32x4*)(an + s * astep + a_voff);
;       rb[s] = *(const u32x4*)(bn + s * bstep + b_voff);
; #pragma unroll
;       for (int mi = 0; mi < 4; ++mi)
; #pragma unroll
;         for (int ni = 0; ni < 2; ++ni) acc[mi][ni] = MFMA32(a[mi], b[ni], acc[mi][ni]);
;     }
;     __syncthreads();
;   }
	ds_read_b128 v[196:199], v194 offset:32768
	ds_read_b128 v[212:215], v160 offset:32768
	ds_read_b128 v[216:219], v160 offset:34816
	ds_read_b128 v[242:245], v160 offset:36864
	ds_read_b128 v[246:249], v160 offset:38912
	ds_read_b128 v[200:203], v194 offset:36864
	ds_read_b128 v[204:207], v194 offset:40960
	ds_read_b128 v[208:211], v194 offset:45056
	s_add_i32 s56, s56, 1
	s_add_u32 m0, s59, 0x0
	s_nop 0
	global_load_lds_dwordx4 v164, s[54:55]
	global_load_lds_dwordx4 v165, s[54:55] offset:1024
	global_load_lds_dwordx4 v130, s[54:55] offset:2048
	global_load_lds_dwordx4 v131, s[54:55] offset:3072
	s_waitcnt lgkmcnt(0)
	v_mfma_f32_16x16x32_bf16 v[114:117], v[196:199], v[212:215], v[114:117]
	ds_read_b128 v[220:223], v194 offset:34816
	v_mfma_f32_16x16x32_bf16 v[118:121], v[196:199], v[216:219], v[118:121]
	ds_read_b128 v[224:227], v194 offset:38912
	v_mfma_f32_16x16x32_bf16 v[98:101], v[196:199], v[242:245], v[98:101]
	ds_read_b128 v[228:231], v194 offset:43008
	v_mfma_f32_16x16x32_bf16 v[102:105], v[196:199], v[246:249], v[102:105]
	ds_read_b128 v[238:241], v194 offset:47104
	v_mfma_f32_16x16x32_bf16 v[82:85], v[200:203], v[212:215], v[82:85]
	v_mfma_f32_16x16x32_bf16 v[86:89], v[200:203], v[216:219], v[86:89]
	v_mfma_f32_16x16x32_bf16 v[66:69], v[200:203], v[242:245], v[66:69]
	v_mfma_f32_16x16x32_bf16 v[70:73], v[200:203], v[246:249], v[70:73]
	v_mfma_f32_16x16x32_bf16 v[50:53], v[204:207], v[212:215], v[50:53]
	v_mfma_f32_16x16x32_bf16 v[54:57], v[204:207], v[216:219], v[54:57]
	v_mfma_f32_16x16x32_bf16 v[34:37], v[204:207], v[242:245], v[34:37]
	v_mfma_f32_16x16x32_bf16 v[38:41], v[204:207], v[246:249], v[38:41]
	v_mfma_f32_16x16x32_bf16 v[18:21], v[208:211], v[212:215], v[18:21]
	v_mfma_f32_16x16x32_bf16 v[22:25], v[208:211], v[216:219], v[22:25]
	v_mfma_f32_16x16x32_bf16 v[2:5], v[208:211], v[242:245], v[2:5]
	v_mfma_f32_16x16x32_bf16 v[6:9], v[208:211], v[246:249], v[6:9]
	s_add_u32 m0, s58, 0x0
	s_nop 0
	global_load_lds_dwordx4 v164, s[52:53]
	global_load_lds_dwordx4 v165, s[52:53] offset:1024
	global_load_lds_dwordx4 v130, s[52:53] offset:2048
	global_load_lds_dwordx4 v131, s[52:53] offset:3072
	s_waitcnt lgkmcnt(0)
	v_mfma_f32_16x16x32_bf16 v[122:125], v[220:223], v[212:215], v[122:125]
	ds_read_b128 v[196:199], v195 offset:32768
	v_mfma_f32_16x16x32_bf16 v[126:129], v[220:223], v[216:219], v[126:129]
	ds_read_b128 v[140:143], v161 offset:32768
	v_mfma_f32_16x16x32_bf16 v[106:109], v[220:223], v[242:245], v[106:109]
	ds_read_b128 v[144:147], v161 offset:34816
	v_mfma_f32_16x16x32_bf16 v[110:113], v[220:223], v[246:249], v[110:113]
	ds_read_b128 v[148:151], v161 offset:36864
	v_mfma_f32_16x16x32_bf16 v[90:93], v[224:227], v[212:215], v[90:93]
	ds_read_b128 v[152:155], v161 offset:38912
	v_mfma_f32_16x16x32_bf16 v[94:97], v[224:227], v[216:219], v[94:97]
	ds_read_b128 v[200:203], v195 offset:36864
	v_mfma_f32_16x16x32_bf16 v[74:77], v[224:227], v[242:245], v[74:77]
	ds_read_b128 v[204:207], v195 offset:40960
	v_mfma_f32_16x16x32_bf16 v[78:81], v[224:227], v[246:249], v[78:81]
	ds_read_b128 v[208:211], v195 offset:45056
	v_mfma_f32_16x16x32_bf16 v[58:61], v[228:231], v[212:215], v[58:61]
	v_mfma_f32_16x16x32_bf16 v[62:65], v[228:231], v[216:219], v[62:65]
	v_mfma_f32_16x16x32_bf16 v[42:45], v[228:231], v[242:245], v[42:45]
	v_mfma_f32_16x16x32_bf16 v[46:49], v[228:231], v[246:249], v[46:49]
	v_mfma_f32_16x16x32_bf16 v[26:29], v[238:241], v[212:215], v[26:29]
	v_mfma_f32_16x16x32_bf16 v[30:33], v[238:241], v[216:219], v[30:33]
	v_mfma_f32_16x16x32_bf16 v[10:13], v[238:241], v[242:245], v[10:13]
	v_mfma_f32_16x16x32_bf16 v[14:17], v[238:241], v[246:249], v[14:17]
	s_waitcnt lgkmcnt(0)
	v_mfma_f32_16x16x32_bf16 v[114:117], v[196:199], v[140:143], v[114:117]
	ds_read_b128 v[220:223], v195 offset:34816
	v_mfma_f32_16x16x32_bf16 v[118:121], v[196:199], v[144:147], v[118:121]
	ds_read_b128 v[224:227], v195 offset:38912
	v_mfma_f32_16x16x32_bf16 v[98:101], v[196:199], v[148:151], v[98:101]
	ds_read_b128 v[228:231], v195 offset:43008
	v_mfma_f32_16x16x32_bf16 v[102:105], v[196:199], v[152:155], v[102:105]
	ds_read_b128 v[238:241], v195 offset:47104
	v_mfma_f32_16x16x32_bf16 v[82:85], v[200:203], v[140:143], v[82:85]
	v_mfma_f32_16x16x32_bf16 v[86:89], v[200:203], v[144:147], v[86:89]
	v_mfma_f32_16x16x32_bf16 v[66:69], v[200:203], v[148:151], v[66:69]
	v_mfma_f32_16x16x32_bf16 v[70:73], v[200:203], v[152:155], v[70:73]
	v_mfma_f32_16x16x32_bf16 v[50:53], v[204:207], v[140:143], v[50:53]
	v_mfma_f32_16x16x32_bf16 v[54:57], v[204:207], v[144:147], v[54:57]
	s_cmp_lt_u32 s56, s57
	s_cselect_b32 s60, 0x80, 0
	s_add_u32 s52, s52, s60
	s_addc_u32 s53, s53, 0
	s_add_u32 s54, s54, s60
	s_addc_u32 s55, s55, 0
	s_cmp_eq_u32 s56, s63
	s_cselect_b32 s52, s64, s52
	s_cselect_b32 s53, s65, s53
	s_cselect_b32 s54, s66, s54
	s_cselect_b32 s55, s67, s55
	v_mfma_f32_16x16x32_bf16 v[34:37], v[204:207], v[148:151], v[34:37]
	v_mfma_f32_16x16x32_bf16 v[38:41], v[204:207], v[152:155], v[38:41]
	v_mfma_f32_16x16x32_bf16 v[18:21], v[208:211], v[140:143], v[18:21]
	v_mfma_f32_16x16x32_bf16 v[22:25], v[208:211], v[144:147], v[22:25]
	v_mfma_f32_16x16x32_bf16 v[2:5], v[208:211], v[148:151], v[2:5]
	v_mfma_f32_16x16x32_bf16 v[6:9], v[208:211], v[152:155], v[6:9]
	s_waitcnt lgkmcnt(0)
	v_mfma_f32_16x16x32_bf16 v[122:125], v[220:223], v[140:143], v[122:125]
	v_mfma_f32_16x16x32_bf16 v[126:129], v[220:223], v[144:147], v[126:129]
	v_mfma_f32_16x16x32_bf16 v[106:109], v[220:223], v[148:151], v[106:109]
	v_mfma_f32_16x16x32_bf16 v[110:113], v[220:223], v[152:155], v[110:113]
	v_mfma_f32_16x16x32_bf16 v[90:93], v[224:227], v[140:143], v[90:93]
	v_mfma_f32_16x16x32_bf16 v[94:97], v[224:227], v[144:147], v[94:97]
	v_mfma_f32_16x16x32_bf16 v[74:77], v[224:227], v[148:151], v[74:77]
	v_mfma_f32_16x16x32_bf16 v[78:81], v[224:227], v[152:155], v[78:81]
	v_mfma_f32_16x16x32_bf16 v[58:61], v[228:231], v[140:143], v[58:61]
	v_mfma_f32_16x16x32_bf16 v[62:65], v[228:231], v[144:147], v[62:65]
	v_mfma_f32_16x16x32_bf16 v[42:45], v[228:231], v[148:151], v[42:45]
	v_mfma_f32_16x16x32_bf16 v[46:49], v[228:231], v[152:155], v[46:49]
	v_mfma_f32_16x16x32_bf16 v[26:29], v[238:241], v[140:143], v[26:29]
	v_mfma_f32_16x16x32_bf16 v[30:33], v[238:241], v[144:147], v[30:33]
	v_mfma_f32_16x16x32_bf16 v[10:13], v[238:241], v[148:151], v[10:13]
	v_mfma_f32_16x16x32_bf16 v[14:17], v[238:241], v[152:155], v[14:17]
	s_waitcnt vmcnt(0)
	s_barrier
; #define MFMA32(a, b, c) __builtin_amdgcn_mfma_f32_32x32x16_bf16((a), (b), (c), 0, 0, 0)
; DI void gemm256(const char* a_u, unsigned a_voff, size_t astep, const char* b_u, unsigned b_voff, size_t bstep, int nk, char* smem, f32x16 (&acc)[4][2]) {
;     ...
;   for (int kt = 0; kt < nk; ++kt) {
;     const int cur = kt & 1, k2 = (kt + 2 < last) ? kt + 2 : last;
;     const char* S = smem + cur * 2 * T2;
;     char* D = smem + (cur ^ 1) * 2 * T2;
;     const char* an = a_u + (size_t)k2 * 128;
;     const char* bn = b_u + (size_t)k2 * 128;
; #pragma unroll
;     for (int s = 0; s < 4; ++s) {
;       bf16x8 a[4], b[2];
; #pragma unroll
;       for (int mi = 0; mi < 4; ++mi) a[mi] = *(const bf16x8*)(S + aoff + mi * 32 * LROW + s * 32);
; #pragma unroll
;       for (int ni = 0; ni < 2; ++ni) b[ni] = *(const bf16x8*)(S + boff + ni * 32 * LROW + s * 32);
;       *(u32x4*)(D + soff + s * 64 * LROW) = ra[s];
;       *(u32x4*)(D + T2 + soff + s * 64 * LROW) = rb[s];
;       ra[s] = *(const u32x4*)(an + s * astep + a_voff);
;       rb[s] = *(const u32x4*)(bn + s * bstep + b_voff);
; #pragma unroll
;       for (int mi = 0; mi < 4; ++mi)
; #pragma unroll
;         for (int ni = 0; ni < 2; ++ni) acc[mi][ni] = MFMA32(a[mi], b[ni], acc[mi][ni]);
;     }
;     __syncthreads();
;   }
	ds_read_b128 v[196:199], v194 offset:0
	ds_read_b128 v[212:215], v160 offset:0
	ds_read_b128 v[216:219], v160 offset:2048
	ds_read_b128 v[242:245], v160 offset:4096
	ds_read_b128 v[246:249], v160 offset:6144
	ds_read_b128 v[200:203], v194 offset:4096
	ds_read_b128 v[204:207], v194 offset:8192
	ds_read_b128 v[208:211], v194 offset:12288
	s_cmp_lt_u32 s56, s57
	s_cbranch_scc1 .Lg_gateup_loop
	s_waitcnt vmcnt(0) lgkmcnt(0)
	s_nop 7
	s_nop 7
	v_permlane16_swap_b32_e32 v114, v118
	v_permlane16_swap_b32_e32 v115, v119
	v_permlane16_swap_b32_e32 v116, v120
	v_permlane16_swap_b32_e32 v117, v121
	v_permlane16_swap_b32_e32 v122, v126
	v_permlane16_swap_b32_e32 v123, v127
	v_permlane16_swap_b32_e32 v124, v128
	v_permlane16_swap_b32_e32 v125, v129
	v_permlane16_swap_b32_e32 v98, v102
	v_permlane16_swap_b32_e32 v99, v103
	v_permlane16_swap_b32_e32 v100, v104
	v_permlane16_swap_b32_e32 v101, v105
	v_permlane16_swap_b32_e32 v106, v110
	v_permlane16_swap_b32_e32 v107, v111
	v_permlane16_swap_b32_e32 v108, v112
	v_permlane16_swap_b32_e32 v109, v113
	v_permlane16_swap_b32_e32 v82, v86
	v_permlane16_swap_b32_e32 v83, v87
	v_permlane16_swap_b32_e32 v84, v88
	v_permlane16_swap_b32_e32 v85, v89
	v_permlane16_swap_b32_e32 v90, v94
	v_permlane16_swap_b32_e32 v91, v95
	v_permlane16_swap_b32_e32 v92, v96
	v_permlane16_swap_b32_e32 v93, v97
	v_permlane16_swap_b32_e32 v66, v70
	v_permlane16_swap_b32_e32 v67, v71
	v_permlane16_swap_b32_e32 v68, v72
	v_permlane16_swap_b32_e32 v69, v73
	v_permlane16_swap_b32_e32 v74, v78
	v_permlane16_swap_b32_e32 v75, v79
	v_permlane16_swap_b32_e32 v76, v80
	v_permlane16_swap_b32_e32 v77, v81
	v_permlane16_swap_b32_e32 v50, v54
	v_permlane16_swap_b32_e32 v51, v55
	v_permlane16_swap_b32_e32 v52, v56
	v_permlane16_swap_b32_e32 v53, v57
	v_permlane16_swap_b32_e32 v58, v62
	v_permlane16_swap_b32_e32 v59, v63
	v_permlane16_swap_b32_e32 v60, v64
	v_permlane16_swap_b32_e32 v61, v65
	v_permlane16_swap_b32_e32 v34, v38
	v_permlane16_swap_b32_e32 v35, v39
	v_permlane16_swap_b32_e32 v36, v40
	v_permlane16_swap_b32_e32 v37, v41
	v_permlane16_swap_b32_e32 v42, v46
	v_permlane16_swap_b32_e32 v43, v47
	v_permlane16_swap_b32_e32 v44, v48
	v_permlane16_swap_b32_e32 v45, v49
	v_permlane16_swap_b32_e32 v18, v22
	v_permlane16_swap_b32_e32 v19, v23
	v_permlane16_swap_b32_e32 v20, v24
	v_permlane16_swap_b32_e32 v21, v25
	v_permlane16_swap_b32_e32 v26, v30
	v_permlane16_swap_b32_e32 v27, v31
	v_permlane16_swap_b32_e32 v28, v32
	v_permlane16_swap_b32_e32 v29, v33
	v_permlane16_swap_b32_e32 v2, v6
	v_permlane16_swap_b32_e32 v3, v7
	v_permlane16_swap_b32_e32 v4, v8
	v_permlane16_swap_b32_e32 v5, v9
	v_permlane16_swap_b32_e32 v10, v14
	v_permlane16_swap_b32_e32 v11, v15
	v_permlane16_swap_b32_e32 v12, v16
	v_permlane16_swap_b32_e32 v13, v17
	v_permlane32_swap_b32_e32 v114, v118
	v_permlane32_swap_b32_e32 v115, v119
	v_permlane32_swap_b32_e32 v116, v120
	v_permlane32_swap_b32_e32 v117, v121
	v_permlane32_swap_b32_e32 v122, v126
	v_permlane32_swap_b32_e32 v123, v127
	v_permlane32_swap_b32_e32 v124, v128
	v_permlane32_swap_b32_e32 v125, v129
	v_permlane32_swap_b32_e32 v98, v102
	v_permlane32_swap_b32_e32 v99, v103
	v_permlane32_swap_b32_e32 v100, v104
	v_permlane32_swap_b32_e32 v101, v105
	v_permlane32_swap_b32_e32 v106, v110
	v_permlane32_swap_b32_e32 v107, v111
	v_permlane32_swap_b32_e32 v108, v112
	v_permlane32_swap_b32_e32 v109, v113
	v_permlane32_swap_b32_e32 v82, v86
	v_permlane32_swap_b32_e32 v83, v87
	v_permlane32_swap_b32_e32 v84, v88
	v_permlane32_swap_b32_e32 v85, v89
	v_permlane32_swap_b32_e32 v90, v94
	v_permlane32_swap_b32_e32 v91, v95
	v_permlane32_swap_b32_e32 v92, v96
	v_permlane32_swap_b32_e32 v93, v97
	v_permlane32_swap_b32_e32 v66, v70
	v_permlane32_swap_b32_e32 v67, v71
	v_permlane32_swap_b32_e32 v68, v72
	v_permlane32_swap_b32_e32 v69, v73
	v_permlane32_swap_b32_e32 v74, v78
	v_permlane32_swap_b32_e32 v75, v79
	v_permlane32_swap_b32_e32 v76, v80
	v_permlane32_swap_b32_e32 v77, v81
	v_permlane32_swap_b32_e32 v50, v54
	v_permlane32_swap_b32_e32 v51, v55
	v_permlane32_swap_b32_e32 v52, v56
	v_permlane32_swap_b32_e32 v53, v57
	v_permlane32_swap_b32_e32 v58, v62
	v_permlane32_swap_b32_e32 v59, v63
	v_permlane32_swap_b32_e32 v60, v64
	v_permlane32_swap_b32_e32 v61, v65
	v_permlane32_swap_b32_e32 v34, v38
	v_permlane32_swap_b32_e32 v35, v39
	v_permlane32_swap_b32_e32 v36, v40
	v_permlane32_swap_b32_e32 v37, v41
	v_permlane32_swap_b32_e32 v42, v46
	v_permlane32_swap_b32_e32 v43, v47
	v_permlane32_swap_b32_e32 v44, v48
	v_permlane32_swap_b32_e32 v45, v49
	v_permlane32_swap_b32_e32 v18, v22
	v_permlane32_swap_b32_e32 v19, v23
	v_permlane32_swap_b32_e32 v20, v24
	v_permlane32_swap_b32_e32 v21, v25
	v_permlane32_swap_b32_e32 v26, v30
	v_permlane32_swap_b32_e32 v27, v31
	v_permlane32_swap_b32_e32 v28, v32
	v_permlane32_swap_b32_e32 v29, v33
	v_permlane32_swap_b32_e32 v2, v6
	v_permlane32_swap_b32_e32 v3, v7
	v_permlane32_swap_b32_e32 v4, v8
	v_permlane32_swap_b32_e32 v5, v9
	v_permlane32_swap_b32_e32 v10, v14
	v_permlane32_swap_b32_e32 v11, v15
	v_permlane32_swap_b32_e32 v12, v16
	v_permlane32_swap_b32_e32 v13, v17
	s_nop 1
	s_branch .LBB0_1568

; DI int tid512() { int t = threadIdx.x; asm volatile("" : "+v"(t)); return t; }
; DI unsigned voff256(size_t ld) { const int t = tid512(); return (unsigned)(((size_t)(t >> 3) * ld + (t & 7) * 8) * 2); }
; DI void gemm256(const char* a_u, unsigned a_voff, size_t astep, const char* b_u, unsigned b_voff, size_t bstep, int nk, char* smem, f32x16 (&acc)[4][2]) {
;   asm volatile("" : "+s"(nk));
;   const int t = tid512(), lane = t & 63, w = t >> 6, wm = w >> 2, wn = w & 3, r = lane & 31, h = lane >> 5;
;   const int soff = (t >> 3) * LROW + (t & 7) * 16;
;   const int aoff = (128 * wm + r) * LROW + h * 16, boff = T2 + (64 * wn + r) * LROW + h * 16;
;   u32x4 ra[4], rb[4];
; #pragma unroll
;   for (int i = 0; i < 4; ++i) { ra[i] = *(const u32x4*)(a_u + i * astep + a_voff); rb[i] = *(const u32x4*)(b_u + i * bstep + b_voff); }
;   __syncthreads();
; #pragma unroll
;   for (int i = 0; i < 4; ++i) { *(u32x4*)(smem + soff + i * 64 * LROW) = ra[i]; *(u32x4*)(smem + T2 + soff + i * 64 * LROW) = rb[i]; }
;   const int last = nk - 1;
;   {
;     const int k1 = last < 1 ? last : 1;
; #pragma unroll
;     for (int i = 0; i < 4; ++i) { ra[i] = *(const u32x4*)(a_u + i * astep + k1 * 128 + a_voff); rb[i] = *(const u32x4*)(b_u + i * bstep + k1 * 128 + b_voff); }
;   }
;   __syncthreads();
; DI void down256(const Params& p, int layer, char* smem) {
;     ...
;     const int L = tile_of(i, 32 * 8);
;     if (L < 0) break;
;     int tm, tn; tile_mn(L, 32, 8, tm, tn);
;     f32x16 acc[4][2]; zero_acc256(acc);
;     gemm256((const char*)(HID + (size_t)(256 + tm * 256) * DFF), voff256(DFF), (size_t)128 * DFF, (const char*)(W + (size_t)(tn * 256) * DFF), voff256(DFF), (size_t)128 * DFF, DFF / 64, smem, acc);
.LBB0_1642:
	s_lshr_b32 s4, s6, 3
	s_and_b32 s4, s4, 0xffffffc
	s_sub_i32 s5, 32, s4
	s_min_i32 s5, s5, 4
	s_abs_i32 s11, s5
	v_cvt_f32_u32_e32 v2, s11
	s_sub_i32 s12, 0, s11
	s_and_b32 s7, s6, 31
	s_ashr_i32 s6, s5, 31
	v_rcp_iflag_f32_e32 v2, v2
	v_mov_b32_e32 v37, v181
	v_mul_f32_e32 v2, 0x4f7ffffe, v2
	v_cvt_u32_f32_e32 v2, v2
	s_nop 0
	v_readfirstlane_b32 s13, v2
	s_mul_i32 s12, s12, s13
	s_mul_hi_u32 s12, s13, s12
	s_add_i32 s13, s13, s12
	s_mul_hi_u32 s12, s7, s13
	s_mul_i32 s13, s12, s11
	s_sub_i32 s13, s7, s13
	s_add_i32 s14, s12, 1
	s_sub_i32 s15, s13, s11
	s_cmp_ge_u32 s13, s11
	s_cselect_b32 s12, s14, s12
	s_cselect_b32 s13, s15, s13
	s_add_i32 s14, s12, 1
	s_cmp_ge_u32 s13, s11
	s_cselect_b32 s11, s14, s12
	s_xor_b32 s11, s11, s6
	s_sub_i32 s6, s11, s6
	s_mul_i32 s5, s6, s5
	s_sub_i32 s5, s7, s5
	v_mov_b32_e32 v2, v0
	s_add_i32 s5, s5, s4
	s_lshl_b32 s11, s5, 8
	v_lshrrev_b32_e32 v3, 3, v2
	v_lshlrev_b32_e32 v2, 3, v2
	v_mul_lo_u32 v3, v3, s34
	s_addk_i32 s11, 0x100
	v_and_or_b32 v2, v2, 56, v3
	s_mul_i32 s4, s11, 0x2c00
	v_readlane_b32 s12, v254, 34
	v_lshlrev_b32_e32 v180, 1, v2
	v_mov_b32_e32 v2, v0
	s_mul_hi_u32 s5, s11, 0x2c00
	v_readlane_b32 s13, v254, 35
	s_add_u32 s4, s12, s4
	s_addc_u32 s5, s13, s5
	v_lshrrev_b32_e32 v3, 3, v2
	s_lshl_b32 s12, s6, 8
	s_mul_i32 s6, s6, 0x2c0000
	v_lshlrev_b32_e32 v2, 3, v2
	v_mul_lo_u32 v3, v3, s34
	s_mul_hi_i32 s7, s12, 0x2c00
	s_add_u32 s6, s8, s6
	v_and_or_b32 v2, v2, 56, v3
	v_lshl_add_u64 v[162:163], s[4:5], 0, v[180:181]
	s_addc_u32 s7, s9, s7
	v_lshlrev_b32_e32 v36, 1, v2
	v_add_co_u32_e32 v12, vcc, s26, v162
	v_lshl_add_u64 v[164:165], s[6:7], 0, v[36:37]
	s_nop 0
	v_addc_co_u32_e32 v13, vcc, 0, v163, vcc
	v_add_co_u32_e32 v16, vcc, s26, v164
	s_movk_i32 s13, 0x58
	v_mov_b32_e32 v2, v0
	v_addc_co_u32_e32 v17, vcc, 0, v165, vcc
	v_add_co_u32_e32 v20, vcc, s86, v162
	v_lshlrev_b32_e32 v4, 4, v2
	v_and_b32_e32 v38, 0x70, v4
	v_lshrrev_b32_e32 v132, 6, v0
	s_nop 0
	v_readfirstlane_b32 s61, v132
	v_and_b32_e32 v132, 63, v0
	v_and_b32_e32 v133, 15, v132
	v_lshrrev_b32_e32 v136, 4, v132
	v_bfe_u32 v137, v133, 1, 3
	v_lshlrev_b32_e32 v133, 7, v133
	s_lshr_b32 s60, s61, 2
	s_lshl_b32 s60, s60, 14
	s_add_i32 s60, s60, 16
	s_and_b32 s62, s61, 3
	s_lshl_b32 s62, s62, 13
	s_add_i32 s62, s62, 0x10010
	v_add_u32_e32 v194, 0, v136
	v_xor_b32_e32 v194, v194, v137
	v_lshl_add_u32 v194, v194, 4, v133
	v_add_u32_e32 v160, s62, v194
	v_add_u32_e32 v194, s60, v194
	v_add_u32_e32 v195, 4, v136
	v_xor_b32_e32 v195, v195, v137
	v_lshl_add_u32 v195, v195, 4, v133
	v_add_u32_e32 v161, s62, v195
	v_add_u32_e32 v195, s60, v195
	v_lshrrev_b32_e32 v133, 3, v132
	s_mov_b32 s60, 0x2c00
	v_mul_lo_u32 v133, v133, s60
	v_and_b32_e32 v136, 7, v132
	v_lshrrev_b32_e32 v137, 4, v132
	v_xor_b32_e32 v164, v137, v136
	v_lshl_add_u32 v164, v164, 4, v133
	v_add_u32_e32 v165, 4, v137
	v_xor_b32_e32 v165, v165, v136
	v_lshl_add_u32 v165, v165, 4, v133
	v_add_u32_e32 v165, 0x15c00, v165
	v_xor_b32_e32 v130, v137, v136
	v_lshl_add_u32 v130, v130, 4, v133
	v_add_u32_e32 v130, 0x2b800, v130
	v_add_u32_e32 v131, 4, v137
	v_xor_b32_e32 v131, v131, v136
	v_lshl_add_u32 v131, v131, 4, v133
	v_add_u32_e32 v131, 0x41400, v131
	s_mul_i32 s60, s61, 0x58000
	s_add_u32 s52, s4, s60
	s_addc_u32 s53, s5, 0
	s_add_u32 s54, s6, s60
	s_addc_u32 s55, s7, 0
	s_lshl_b32 s58, s61, 12
	s_add_i32 s58, s58, 16
	s_add_i32 s59, s58, 0x10000
	s_mov_b32 s56, 0
	s_mov_b32 s57, 87
	s_barrier
	s_add_u32 m0, s58, 0x0
	s_nop 0
	global_load_lds_dwordx4 v164, s[52:53]
	global_load_lds_dwordx4 v165, s[52:53] offset:1024
	global_load_lds_dwordx4 v130, s[52:53] offset:2048
	global_load_lds_dwordx4 v131, s[52:53] offset:3072
	s_add_u32 m0, s59, 0x0
	s_nop 0
	global_load_lds_dwordx4 v164, s[54:55]
	global_load_lds_dwordx4 v165, s[54:55] offset:1024
	global_load_lds_dwordx4 v130, s[54:55] offset:2048
	global_load_lds_dwordx4 v131, s[54:55] offset:3072
	s_cmp_lt_u32 s56, s57
	s_cselect_b32 s60, 0x80, 0
	s_add_u32 s52, s52, s60
	s_addc_u32 s53, s53, 0
	s_add_u32 s54, s54, s60
	s_addc_u32 s55, s55, 0
	v_mov_b64_e32 v[114:115], 0
	v_mov_b64_e32 v[116:117], 0
	v_mov_b64_e32 v[118:119], 0
	v_mov_b64_e32 v[120:121], 0
	v_mov_b64_e32 v[122:123], 0
	v_mov_b64_e32 v[124:125], 0
	v_mov_b64_e32 v[126:127], 0
	v_mov_b64_e32 v[128:129], 0
	v_mov_b64_e32 v[98:99], 0
	v_mov_b64_e32 v[100:101], 0
	v_mov_b64_e32 v[102:103], 0
	v_mov_b64_e32 v[104:105], 0
	v_mov_b64_e32 v[106:107], 0
	v_mov_b64_e32 v[108:109], 0
	v_mov_b64_e32 v[110:111], 0
	v_mov_b64_e32 v[112:113], 0
	v_mov_b64_e32 v[82:83], 0
	v_mov_b64_e32 v[84:85], 0
	v_mov_b64_e32 v[86:87], 0
	v_mov_b64_e32 v[88:89], 0
	v_mov_b64_e32 v[90:91], 0
	v_mov_b64_e32 v[92:93], 0
	v_mov_b64_e32 v[94:95], 0
	v_mov_b64_e32 v[96:97], 0
	v_mov_b64_e32 v[66:67], 0
	v_mov_b64_e32 v[68:69], 0
	v_mov_b64_e32 v[70:71], 0
	v_mov_b64_e32 v[72:73], 0
	v_mov_b64_e32 v[74:75], 0
	v_mov_b64_e32 v[76:77], 0
	v_mov_b64_e32 v[78:79], 0
	v_mov_b64_e32 v[80:81], 0
	v_mov_b64_e32 v[50:51], 0
	v_mov_b64_e32 v[52:53], 0
	v_mov_b64_e32 v[54:55], 0
	v_mov_b64_e32 v[56:57], 0
	v_mov_b64_e32 v[58:59], 0
	v_mov_b64_e32 v[60:61], 0
	v_mov_b64_e32 v[62:63], 0
	v_mov_b64_e32 v[64:65], 0
	v_mov_b64_e32 v[34:35], 0
	v_mov_b64_e32 v[36:37], 0
	v_mov_b64_e32 v[38:39], 0
	v_mov_b64_e32 v[40:41], 0
	v_mov_b64_e32 v[42:43], 0
	v_mov_b64_e32 v[44:45], 0
	v_mov_b64_e32 v[46:47], 0
	v_mov_b64_e32 v[48:49], 0
	v_mov_b64_e32 v[18:19], 0
	v_mov_b64_e32 v[20:21], 0
	v_mov_b64_e32 v[22:23], 0
	v_mov_b64_e32 v[24:25], 0
	v_mov_b64_e32 v[26:27], 0
	v_mov_b64_e32 v[28:29], 0
	v_mov_b64_e32 v[30:31], 0
	v_mov_b64_e32 v[32:33], 0
	v_mov_b64_e32 v[2:3], 0
	v_mov_b64_e32 v[4:5], 0
	v_mov_b64_e32 v[6:7], 0
	v_mov_b64_e32 v[8:9], 0
	v_mov_b64_e32 v[10:11], 0
	v_mov_b64_e32 v[12:13], 0
	v_mov_b64_e32 v[14:15], 0
	v_mov_b64_e32 v[16:17], 0
	s_waitcnt vmcnt(0)
	s_barrier
	ds_read_b128 v[196:199], v194 offset:0
	ds_read_b128 v[212:215], v160 offset:0
	ds_read_b128 v[216:219], v160 offset:2048
	ds_read_b128 v[242:245], v160 offset:4096
	ds_read_b128 v[246:249], v160 offset:6144
	ds_read_b128 v[200:203], v194 offset:4096
	ds_read_b128 v[204:207], v194 offset:8192
	ds_read_b128 v[208:211], v194 offset:12288
